# P8 edits + EpiUp (P4/P11 epilogue): row-invariant part of the output address hoisted once per tile (removes 3 of 4 address VALU ops at 14 row stores per tile, VALU-bound epilogue)
# speedup vs baseline: 1.0064x; 1.0021x over previous
; #define LAS __attribute__((address_space(3)))
; __device__ __forceinline__ unsigned pkh(float lo, float hi) { f32x2 v = {lo, hi}; h16x2 h = __builtin_convertvector(v, h16x2); return __builtin_bit_cast(unsigned, h); }
;     __device__ __forceinline__ void operator()(f32x4 (&acc)[2][2][4][2], const Unit& u, const Order& S, int wr, int wc, int fr_, int fq_, LAS unsigned char* xl, int ui) const {
;     ...
;                     f32x4 r63 = {0.f, 0.f, 0.f, 0.f}, r62 = r63;
;                     if (g > 0) { r62 = *(const LAS f32x4*)(bnd + ((g - 1) * 2 + 0) * 256 + bj * HALF + tcol + 16 * n); r63 = *(const LAS f32x4*)(bnd + ((g - 1) * 2 + 1) * 256 + bj * HALF + tcol + 16 * n); }
;                     const f32x4 x0 = acc[ai][bj][0][n], x1 = acc[ai][bj][1][n], x2 = acc[ai][bj][2][n], x3 = acc[ai][bj][3][n];
;                     f32x4 pm1, pm2;
; #pragma unroll
;                     for (int e = 0; e < 4; ++e) { pm1[e] = dpp_shr1_keep(r63[e], x3[e]); pm2[e] = dpp_shr1_keep(r62[e], x2[e]); }
;                     h[0][bj] = __builtin_elementwise_fma(w0[bj], pm2, __builtin_elementwise_fma(w1[bj], pm1, __builtin_elementwise_fma(w2[bj], x0, bb[bj])));
;                     h[1][bj] = __builtin_elementwise_fma(w0[bj], pm1, __builtin_elementwise_fma(w1[bj], x0, __builtin_elementwise_fma(w2[bj], x1, bb[bj])));
;                     h[2][bj] = __builtin_elementwise_fma(w0[bj], x0, __builtin_elementwise_fma(w1[bj], x1, __builtin_elementwise_fma(w2[bj], x2, bb[bj])));
;                     h[3][bj] = __builtin_elementwise_fma(w0[bj], x1, __builtin_elementwise_fma(w1[bj], x2, __builtin_elementwise_fma(w2[bj], x3, bb[bj])));
;                 }
; #pragma unroll
;                 for (int m = 0; m < 4; ++m) {
;                     f32x4 o; { const f32x2 g0 = gelu_tanh2((f32x2){h[m][0][0], h[m][0][1]}) * (f32x2){h[m][1][0], h[m][1][1]}, g1 = gelu_tanh2((f32x2){h[m][0][2], h[m][0][3]}) * (f32x2){h[m][1][2], h[m][1][3]}; o = (f32x4){g0.x, g0.y, g1.x, g1.y}; }
;                     const int trow = trow0 + ai * HALF + m;
;                     if (trow >= lo) { u32x2 pk; pk.x = pkh(o[0], o[1]); pk.y = pkh(o[2], o[3]); *(u32x2*)(U + (size_t)(rs + trow) * FF + u.pn * HALF + tcol + 16 * n) = pk; }
.LBB0_506:
	s_lshl_b32 s48, s4, 7
	s_lshl_b32 s43, s14, 8
	s_ashr_i32 s49, s48, 31
	v_mov_b64_e32 v[240:241], s[58:59]
	v_lshl_add_u64 v[240:241], s[48:49], 1, v[240:241]
	v_lshl_add_u64 v[240:241], v[204:205], 1, v[240:241]
	s_waitcnt lgkmcnt(0)
	v_mov_b32_dpp v170, v146 row_shr:1 row_mask:0xf bank_mask:0xf
	v_mov_b32_dpp v178, v142 row_shr:1 row_mask:0xf bank_mask:0xf
	v_mov_b32_dpp v171, v147 row_shr:1 row_mask:0xf bank_mask:0xf
	v_mov_b32_dpp v179, v143 row_shr:1 row_mask:0xf bank_mask:0xf
	v_mov_b32_dpp v172, v148 row_shr:1 row_mask:0xf bank_mask:0xf
	v_mov_b32_dpp v180, v144 row_shr:1 row_mask:0xf bank_mask:0xf
	v_mov_b32_dpp v173, v149 row_shr:1 row_mask:0xf bank_mask:0xf
	v_mov_b32_dpp v181, v145 row_shr:1 row_mask:0xf bank_mask:0xf
	v_cmp_lt_i32_e64 s[8:9], 1, v215
	v_add_u32_e32 v216, s43, v215
	s_and_saveexec_b64 s[4:5], s[8:9]
	s_cbranch_execz .LBB0_508
	v_pk_fma_f32 v[132:133], v[124:125], v[160:161], v[128:129]
	v_pk_fma_f32 v[220:221], v[122:123], v[158:159], v[126:127]
	v_pk_fma_f32 v[132:133], v[120:121], v[168:169], v[132:133]
	v_pk_fma_f32 v[220:221], v[118:119], v[166:167], v[220:221]
	v_pk_fma_f32 v[132:133], v[108:109], v[176:177], v[132:133]
	v_pk_fma_f32 v[174:175], v[106:107], v[174:175], v[220:221]
	v_pk_mul_f32 v[222:223], v[132:133], v[132:133]
	v_pk_mul_f32 v[224:225], v[174:175], v[174:175]
	v_mov_b64_e32 v[226:227], s[40:41]
	v_pk_fma_f32 v[222:223], v[222:223], s[38:39], v[226:227] op_sel_hi:[1,0,0] neg_lo:[1,0,0] neg_hi:[1,0,0]
	v_pk_fma_f32 v[224:225], v[224:225], s[38:39], v[226:227] op_sel_hi:[1,0,0] neg_lo:[1,0,0] neg_hi:[1,0,0]
	v_pk_mul_f32 v[222:223], v[132:133], v[222:223]
	v_pk_mul_f32 v[224:225], v[174:175], v[224:225]
	v_exp_f32_e32 v222, v222
	v_exp_f32_e32 v223, v223
	v_exp_f32_e32 v224, v224
	v_exp_f32_e32 v225, v225
	v_pk_fma_f32 v[176:177], v[112:113], v[164:165], v[116:117]
	v_pk_add_f32 v[222:223], v[222:223], 1.0 op_sel_hi:[1,0]
	v_pk_fma_f32 v[220:221], v[110:111], v[162:163], v[114:115]
	v_pk_add_f32 v[224:225], v[224:225], 1.0 op_sel_hi:[1,0]
	v_rcp_f32_e32 v222, v222
	v_rcp_f32_e32 v223, v223
	v_rcp_f32_e32 v224, v224
	v_rcp_f32_e32 v225, v225
	v_pk_fma_f32 v[176:177], v[104:105], v[172:173], v[176:177]
	v_pk_fma_f32 v[220:221], v[102:103], v[170:171], v[220:221]
	v_pk_fma_f32 v[176:177], v[100:101], v[180:181], v[176:177]
	v_pk_fma_f32 v[178:179], v[98:99], v[178:179], v[220:221]
	v_pk_mul_f32 v[132:133], v[132:133], v[222:223]
	v_pk_mul_f32 v[174:175], v[174:175], v[224:225]
	v_pk_mul_f32 v[132:133], v[132:133], v[176:177]
	v_pk_mul_f32 v[174:175], v[174:175], v[178:179]
	s_nop 0
	v_cvt_pk_f16_f32 v174, v174, v175
	v_cvt_pk_f16_f32 v175, v132, v133
	v_mad_i64_i32 v[132:133], s[6:7], v216, s86, v[240:241]
	global_store_dwordx2 v[132:133], v[174:175], off
.LBB0_508:
	s_or_b64 exec, exec, s[4:5]
	v_or_b32_e32 v132, 1, v215
	v_cmp_lt_i32_e64 s[4:5], 0, v215
	v_add_u32_e32 v174, s43, v132
	s_and_saveexec_b64 s[6:7], s[4:5]
	s_cbranch_execz .LBB0_510
	v_pk_fma_f32 v[132:133], v[112:113], v[152:153], v[116:117]
	v_mov_b64_e32 v[178:179], s[40:41]
	v_pk_fma_f32 v[132:133], v[104:105], v[164:165], v[132:133]
	v_pk_fma_f32 v[176:177], v[110:111], v[150:151], v[114:115]
	v_pk_fma_f32 v[132:133], v[100:101], v[172:173], v[132:133]
	v_pk_fma_f32 v[172:173], v[124:125], v[156:157], v[128:129]
	v_pk_fma_f32 v[176:177], v[102:103], v[162:163], v[176:177]
	v_pk_fma_f32 v[172:173], v[120:121], v[160:161], v[172:173]
	v_pk_fma_f32 v[170:171], v[98:99], v[170:171], v[176:177]
	v_pk_fma_f32 v[168:169], v[108:109], v[168:169], v[172:173]
	v_pk_fma_f32 v[176:177], v[122:123], v[154:155], v[126:127]
	v_pk_mul_f32 v[172:173], v[168:169], v[168:169]
	v_pk_fma_f32 v[176:177], v[118:119], v[158:159], v[176:177]
	v_pk_fma_f32 v[172:173], v[172:173], s[38:39], v[178:179] op_sel_hi:[1,0,0] neg_lo:[1,0,0] neg_hi:[1,0,0]
	v_pk_fma_f32 v[166:167], v[106:107], v[166:167], v[176:177]
	v_pk_mul_f32 v[172:173], v[168:169], v[172:173]
	v_pk_mul_f32 v[176:177], v[166:167], v[166:167]
	v_exp_f32_e32 v172, v172
	v_exp_f32_e32 v173, v173
	s_nop 0
	v_pk_add_f32 v[172:173], v[172:173], 1.0 op_sel_hi:[1,0]
	s_nop 0
	v_rcp_f32_e32 v172, v172
	v_rcp_f32_e32 v173, v173
	s_nop 0
	v_pk_mul_f32 v[168:169], v[168:169], v[172:173]
	v_pk_fma_f32 v[172:173], v[176:177], s[38:39], v[178:179] op_sel_hi:[1,0,0] neg_lo:[1,0,0] neg_hi:[1,0,0]
	v_pk_mul_f32 v[132:133], v[168:169], v[132:133]
	v_pk_mul_f32 v[172:173], v[166:167], v[172:173]
	s_nop 0
	v_exp_f32_e32 v172, v172
	v_exp_f32_e32 v173, v173
	s_nop 0
	v_pk_add_f32 v[172:173], v[172:173], 1.0 op_sel_hi:[1,0]
	s_nop 0
	v_rcp_f32_e32 v172, v172
	v_rcp_f32_e32 v173, v173
	s_nop 0
	v_pk_mul_f32 v[166:167], v[166:167], v[172:173]
	s_nop 0
	v_pk_mul_f32 v[166:167], v[166:167], v[170:171]
	s_nop 0
	v_cvt_pk_f16_f32 v166, v166, v167
	v_cvt_pk_f16_f32 v167, v132, v133
	v_mad_i64_i32 v[132:133], s[10:11], v174, s86, v[240:241]
	global_store_dwordx2 v[132:133], v[166:167], off
; #define LAS __attribute__((address_space(3)))
;     __device__ __forceinline__ void operator()(f32x4 (&acc)[2][2][4][2], const Unit& u, const Order& S, int wr, int wc, int fr_, int fq_, LAS unsigned char* xl, int ui) const {
;     ...
;             const f32x4 ss4 = *(const LAS f32x4*)(cst + 1024 + trow0 + ai * HALF);
; #pragma unroll
;             for (int m = 0; m < 4; ++m) {
;                 const float sc = __builtin_amdgcn_rsqf(ss4[m] * (1.0f / DM) + EPS);
; #pragma unroll
;                 for (int bj = 0; bj < 2; ++bj)
; #pragma unroll
;                     for (int n = 0; n < 2; ++n) acc[ai][bj][m][n] *= sc;
;     ...
;                     if (g > 0) { r62 = *(const LAS f32x4*)(bnd + ((g - 1) * 2 + 0) * 256 + bj * HALF + tcol + 16 * n); r63 = *(const LAS f32x4*)(bnd + ((g - 1) * 2 + 1) * 256 + bj * HALF + tcol + 16 * n); }
;                     const f32x4 x0 = acc[ai][bj][0][n], x1 = acc[ai][bj][1][n], x2 = acc[ai][bj][2][n], x3 = acc[ai][bj][3][n];
;                     f32x4 pm1, pm2;
; #pragma unroll
;                     for (int e = 0; e < 4; ++e) { pm1[e] = dpp_shr1_keep(r63[e], x3[e]); pm2[e] = dpp_shr1_keep(r62[e], x2[e]); }
;                     h[0][bj] = __builtin_elementwise_fma(w0[bj], pm2, __builtin_elementwise_fma(w1[bj], pm1, __builtin_elementwise_fma(w2[bj], x0, bb[bj])));
;                     h[1][bj] = __builtin_elementwise_fma(w0[bj], pm1, __builtin_elementwise_fma(w1[bj], x0, __builtin_elementwise_fma(w2[bj], x1, bb[bj])));
;                     h[2][bj] = __builtin_elementwise_fma(w0[bj], x0, __builtin_elementwise_fma(w1[bj], x1, __builtin_elementwise_fma(w2[bj], x2, bb[bj])));
;                     h[3][bj] = __builtin_elementwise_fma(w0[bj], x1, __builtin_elementwise_fma(w1[bj], x2, __builtin_elementwise_fma(w2[bj], x3, bb[bj])));
;                 }
; #pragma unroll
;                 for (int m = 0; m < 4; ++m) {
;                     f32x4 o; { const f32x2 g0 = gelu_tanh2((f32x2){h[m][0][0], h[m][0][1]}) * (f32x2){h[m][1][0], h[m][1][1]}, g1 = gelu_tanh2((f32x2){h[m][0][2], h[m][0][3]}) * (f32x2){h[m][1][2], h[m][1][3]}; o = (f32x4){g0.x, g0.y, g1.x, g1.y}; }
;                     const int trow = trow0 + ai * HALF + m;
;                     if (trow >= lo) { u32x2 pk; pk.x = pkh(o[0], o[1]); pk.y = pkh(o[2], o[3]); *(u32x2*)(U + (size_t)(rs + trow) * FF + u.pn * HALF + tcol + 16 * n) = pk; }
.LBB0_510:
	s_or_b64 exec, exec, s[6:7]
	v_or_b32_e32 v132, 2, v215
	v_cmp_lt_i32_e64 s[6:7], -1, v215
	v_add_u32_e32 v166, s43, v132
	s_and_saveexec_b64 s[10:11], s[6:7]
	s_cbranch_execz .LBB0_512
	v_pk_fma_f32 v[132:133], v[112:113], v[144:145], v[116:117]
	v_mov_b64_e32 v[170:171], s[40:41]
	v_pk_fma_f32 v[132:133], v[104:105], v[152:153], v[132:133]
	v_pk_fma_f32 v[168:169], v[110:111], v[142:143], v[114:115]
	v_pk_fma_f32 v[132:133], v[100:101], v[164:165], v[132:133]
	v_pk_fma_f32 v[164:165], v[124:125], v[136:137], v[128:129]
	v_pk_fma_f32 v[168:169], v[102:103], v[150:151], v[168:169]
	v_pk_fma_f32 v[164:165], v[120:121], v[156:157], v[164:165]
	v_pk_fma_f32 v[162:163], v[98:99], v[162:163], v[168:169]
	v_pk_fma_f32 v[160:161], v[108:109], v[160:161], v[164:165]
	v_pk_fma_f32 v[168:169], v[122:123], v[134:135], v[126:127]
	v_pk_mul_f32 v[164:165], v[160:161], v[160:161]
	v_pk_fma_f32 v[168:169], v[118:119], v[154:155], v[168:169]
	v_pk_fma_f32 v[164:165], v[164:165], s[38:39], v[170:171] op_sel_hi:[1,0,0] neg_lo:[1,0,0] neg_hi:[1,0,0]
	v_pk_fma_f32 v[158:159], v[106:107], v[158:159], v[168:169]
	v_pk_mul_f32 v[164:165], v[160:161], v[164:165]
	v_pk_mul_f32 v[168:169], v[158:159], v[158:159]
	v_exp_f32_e32 v164, v164
	v_exp_f32_e32 v165, v165
	s_nop 0
	v_pk_add_f32 v[164:165], v[164:165], 1.0 op_sel_hi:[1,0]
	s_nop 0
	v_rcp_f32_e32 v164, v164
	v_rcp_f32_e32 v165, v165
	s_nop 0
	v_pk_mul_f32 v[160:161], v[160:161], v[164:165]
	v_pk_fma_f32 v[164:165], v[168:169], s[38:39], v[170:171] op_sel_hi:[1,0,0] neg_lo:[1,0,0] neg_hi:[1,0,0]
	v_pk_mul_f32 v[132:133], v[132:133], v[160:161]
	v_pk_mul_f32 v[164:165], v[158:159], v[164:165]
	s_nop 0
	v_exp_f32_e32 v164, v164
	v_exp_f32_e32 v165, v165
	s_nop 0
	v_pk_add_f32 v[164:165], v[164:165], 1.0 op_sel_hi:[1,0]
	s_nop 0
	v_rcp_f32_e32 v164, v164
	v_rcp_f32_e32 v165, v165
	s_nop 0
	v_pk_mul_f32 v[158:159], v[158:159], v[164:165]
	s_nop 0
	v_pk_mul_f32 v[158:159], v[162:163], v[158:159]
	s_nop 0
	v_cvt_pk_f16_f32 v158, v158, v159
	v_cvt_pk_f16_f32 v159, v132, v133
	v_mad_i64_i32 v[132:133], s[12:13], v166, s86, v[240:241]
	global_store_dwordx2 v[132:133], v[158:159], off
.LBB0_512:
	s_or_b64 exec, exec, s[10:11]
	v_or_b32_e32 v132, 3, v215
	v_add_u32_e32 v158, s43, v132
	s_and_saveexec_b64 s[10:11], s[6:7]
	s_cbranch_execz .LBB0_514
	v_pk_fma_f32 v[140:141], v[124:125], v[140:141], v[128:129]
	v_pk_fma_f32 v[138:139], v[122:123], v[138:139], v[126:127]
	v_pk_fma_f32 v[136:137], v[120:121], v[136:137], v[140:141]
	v_pk_fma_f32 v[134:135], v[118:119], v[134:135], v[138:139]
	v_pk_fma_f32 v[132:133], v[112:113], v[148:149], v[116:117]
	v_pk_fma_f32 v[136:137], v[108:109], v[156:157], v[136:137]
	v_pk_fma_f32 v[134:135], v[106:107], v[154:155], v[134:135]
	v_pk_fma_f32 v[132:133], v[104:105], v[144:145], v[132:133]
	v_pk_mul_f32 v[138:139], v[136:137], v[136:137]
	v_pk_mul_f32 v[140:141], v[134:135], v[134:135]
	v_mov_b64_e32 v[144:145], s[40:41]
	v_pk_fma_f32 v[138:139], v[138:139], s[38:39], v[144:145] op_sel_hi:[1,0,0] neg_lo:[1,0,0] neg_hi:[1,0,0]
	v_pk_fma_f32 v[140:141], v[140:141], s[38:39], v[144:145] op_sel_hi:[1,0,0] neg_lo:[1,0,0] neg_hi:[1,0,0]
	v_pk_mul_f32 v[138:139], v[136:137], v[138:139]
	v_pk_mul_f32 v[140:141], v[134:135], v[140:141]
	v_exp_f32_e32 v138, v138
	v_exp_f32_e32 v139, v139
	v_exp_f32_e32 v140, v140
	v_exp_f32_e32 v141, v141
	v_pk_fma_f32 v[146:147], v[110:111], v[146:147], v[114:115]
	v_pk_add_f32 v[138:139], v[138:139], 1.0 op_sel_hi:[1,0]
	v_pk_fma_f32 v[142:143], v[102:103], v[142:143], v[146:147]
	v_pk_add_f32 v[140:141], v[140:141], 1.0 op_sel_hi:[1,0]
	v_rcp_f32_e32 v138, v138
	v_rcp_f32_e32 v139, v139
	v_rcp_f32_e32 v140, v140
	v_rcp_f32_e32 v141, v141
	v_pk_fma_f32 v[132:133], v[100:101], v[152:153], v[132:133]
	v_pk_fma_f32 v[142:143], v[98:99], v[150:151], v[142:143]
	v_pk_mul_f32 v[136:137], v[136:137], v[138:139]
	v_pk_mul_f32 v[134:135], v[134:135], v[140:141]
	v_pk_mul_f32 v[132:133], v[132:133], v[136:137]
	v_pk_mul_f32 v[134:135], v[142:143], v[134:135]
	s_nop 0
	v_cvt_pk_f16_f32 v134, v134, v135
	v_cvt_pk_f16_f32 v135, v132, v133
	v_mad_i64_i32 v[132:133], s[12:13], v158, s86, v[240:241]
	global_store_dwordx2 v[132:133], v[134:135], off
.LBB0_514:
	s_or_b64 exec, exec, s[10:11]
	v_fmamk_f32 v130, v130, 0x3a800000, v214
	v_rsq_f32_e32 v130, v130
	ds_read_b128 v[132:135], v190 offset:3072
	v_add_u32_e32 v148, 0x80, v215
	s_movk_i32 s10, 0xff81
	v_pk_mul_f32 v[144:145], v[76:77], v[130:131] op_sel_hi:[1,0]
	v_pk_mul_f32 v[146:147], v[74:75], v[130:131] op_sel_hi:[1,0]
	v_pk_mul_f32 v[140:141], v[68:69], v[130:131] op_sel_hi:[1,0]
	ds_read_b128 v[74:77], v190 offset:2048
	ds_read_b128 v[136:139], v190 offset:2560
	v_pk_mul_f32 v[142:143], v[66:67], v[130:131] op_sel_hi:[1,0]
	ds_read_b128 v[66:69], v190 offset:3584
	s_waitcnt lgkmcnt(0)
	v_mov_b32_dpp v132, v94 row_shr:1 row_mask:0xf bank_mask:0xf
	v_mov_b32_dpp v74, v86 row_shr:1 row_mask:0xf bank_mask:0xf
	v_mov_b32_dpp v133, v95 row_shr:1 row_mask:0xf bank_mask:0xf
	v_mov_b32_dpp v75, v87 row_shr:1 row_mask:0xf bank_mask:0xf
	v_mov_b32_dpp v134, v96 row_shr:1 row_mask:0xf bank_mask:0xf
	v_mov_b32_dpp v76, v88 row_shr:1 row_mask:0xf bank_mask:0xf
	v_mov_b32_dpp v135, v97 row_shr:1 row_mask:0xf bank_mask:0xf
	v_mov_b32_dpp v77, v89 row_shr:1 row_mask:0xf bank_mask:0xf
	v_mov_b32_dpp v66, v90 row_shr:1 row_mask:0xf bank_mask:0xf
	v_mov_b32_dpp v136, v82 row_shr:1 row_mask:0xf bank_mask:0xf
	v_mov_b32_dpp v67, v91 row_shr:1 row_mask:0xf bank_mask:0xf
	v_mov_b32_dpp v137, v83 row_shr:1 row_mask:0xf bank_mask:0xf
	v_mov_b32_dpp v68, v92 row_shr:1 row_mask:0xf bank_mask:0xf
	v_mov_b32_dpp v138, v84 row_shr:1 row_mask:0xf bank_mask:0xf
	v_mov_b32_dpp v69, v93 row_shr:1 row_mask:0xf bank_mask:0xf
	v_mov_b32_dpp v139, v85 row_shr:1 row_mask:0xf bank_mask:0xf
	v_cmp_lt_i32_e64 s[10:11], s10, v215
	v_add_u32_e32 v148, s43, v148
	s_and_saveexec_b64 s[12:13], s[10:11]
	s_cbranch_execz .LBB0_516
; __device__ __forceinline__ unsigned pkh(float lo, float hi) { f32x2 v = {lo, hi}; h16x2 h = __builtin_convertvector(v, h16x2); return __builtin_bit_cast(unsigned, h); }
;     __device__ __forceinline__ void operator()(f32x4 (&acc)[2][2][4][2], const Unit& u, const Order& S, int wr, int wc, int fr_, int fq_, LAS unsigned char* xl, int ui) const {
;     ...
;                     h[0][bj] = __builtin_elementwise_fma(w0[bj], pm2, __builtin_elementwise_fma(w1[bj], pm1, __builtin_elementwise_fma(w2[bj], x0, bb[bj])));
;                     h[1][bj] = __builtin_elementwise_fma(w0[bj], pm1, __builtin_elementwise_fma(w1[bj], x0, __builtin_elementwise_fma(w2[bj], x1, bb[bj])));
;                     h[2][bj] = __builtin_elementwise_fma(w0[bj], x0, __builtin_elementwise_fma(w1[bj], x1, __builtin_elementwise_fma(w2[bj], x2, bb[bj])));
;                     h[3][bj] = __builtin_elementwise_fma(w0[bj], x1, __builtin_elementwise_fma(w1[bj], x2, __builtin_elementwise_fma(w2[bj], x3, bb[bj])));
;                 }
; #pragma unroll
;                 for (int m = 0; m < 4; ++m) {
;                     f32x4 o; { const f32x2 g0 = gelu_tanh2((f32x2){h[m][0][0], h[m][0][1]}) * (f32x2){h[m][1][0], h[m][1][1]}, g1 = gelu_tanh2((f32x2){h[m][0][2], h[m][0][3]}) * (f32x2){h[m][1][2], h[m][1][3]}; o = (f32x4){g0.x, g0.y, g1.x, g1.y}; }
;                     const int trow = trow0 + ai * HALF + m;
;                     if (trow >= lo) { u32x2 pk; pk.x = pkh(o[0], o[1]); pk.y = pkh(o[2], o[3]); *(u32x2*)(U + (size_t)(rs + trow) * FF + u.pn * HALF + tcol + 16 * n) = pk; }
	v_pk_fma_f32 v[150:151], v[124:125], v[144:145], v[128:129]
	v_mov_b64_e32 v[154:155], s[40:41]
	v_pk_fma_f32 v[150:151], v[120:121], v[134:135], v[150:151]
	v_pk_fma_f32 v[152:153], v[122:123], v[146:147], v[126:127]
	v_pk_fma_f32 v[76:77], v[108:109], v[76:77], v[150:151]
	v_pk_fma_f32 v[150:151], v[112:113], v[140:141], v[116:117]
	v_pk_fma_f32 v[152:153], v[118:119], v[132:133], v[152:153]
	v_pk_fma_f32 v[150:151], v[104:105], v[68:69], v[150:151]
	v_pk_fma_f32 v[74:75], v[106:107], v[74:75], v[152:153]
	v_pk_fma_f32 v[138:139], v[100:101], v[138:139], v[150:151]
	v_pk_mul_f32 v[150:151], v[76:77], v[76:77]
	v_pk_fma_f32 v[152:153], v[110:111], v[142:143], v[114:115]
	v_pk_fma_f32 v[150:151], v[150:151], s[38:39], v[154:155] op_sel_hi:[1,0,0] neg_lo:[1,0,0] neg_hi:[1,0,0]
	v_pk_fma_f32 v[152:153], v[102:103], v[66:67], v[152:153]
	v_pk_mul_f32 v[150:151], v[76:77], v[150:151]
	v_pk_fma_f32 v[136:137], v[98:99], v[136:137], v[152:153]
	v_exp_f32_e32 v150, v150
	v_exp_f32_e32 v151, v151
	v_pk_mul_f32 v[152:153], v[74:75], v[74:75]
	v_pk_add_f32 v[150:151], v[150:151], 1.0 op_sel_hi:[1,0]
	s_nop 0
	v_rcp_f32_e32 v150, v150
	v_rcp_f32_e32 v151, v151
	s_nop 0
	v_pk_mul_f32 v[76:77], v[76:77], v[150:151]
	v_pk_fma_f32 v[150:151], v[152:153], s[38:39], v[154:155] op_sel_hi:[1,0,0] neg_lo:[1,0,0] neg_hi:[1,0,0]
	v_pk_mul_f32 v[76:77], v[138:139], v[76:77]
	v_pk_mul_f32 v[150:151], v[74:75], v[150:151]
	s_nop 0
	v_exp_f32_e32 v150, v150
	v_exp_f32_e32 v151, v151
	s_nop 0
	v_pk_add_f32 v[150:151], v[150:151], 1.0 op_sel_hi:[1,0]
	s_nop 0
	v_rcp_f32_e32 v150, v150
	v_rcp_f32_e32 v151, v151
	s_nop 0
	v_pk_mul_f32 v[74:75], v[74:75], v[150:151]
	s_nop 0
	v_pk_mul_f32 v[74:75], v[136:137], v[74:75]
	s_nop 0
	v_cvt_pk_f16_f32 v74, v74, v75
	v_cvt_pk_f16_f32 v75, v76, v77
	v_mad_i64_i32 v[76:77], s[14:15], v148, s86, v[240:241]
	global_store_dwordx2 v[76:77], v[74:75], off
.LBB0_516:
	s_or_b64 exec, exec, s[12:13]
	v_fmamk_f32 v74, v131, 0x3a800000, v214
	v_rsq_f32_e32 v136, v74
	v_add_u32_e32 v74, 0x81, v215
	s_movk_i32 s12, 0xff80
	v_cmp_lt_i32_e64 s[12:13], s12, v215
	v_pk_mul_f32 v[40:41], v[40:41], v[136:137] op_sel_hi:[1,0]
	v_pk_mul_f32 v[38:39], v[38:39], v[136:137] op_sel_hi:[1,0]
	v_pk_mul_f32 v[36:37], v[36:37], v[136:137] op_sel_hi:[1,0]
	v_pk_mul_f32 v[34:35], v[34:35], v[136:137] op_sel_hi:[1,0]
	v_add_u32_e32 v138, s43, v74
	s_and_saveexec_b64 s[14:15], s[12:13]
	s_cbranch_execz .LBB0_518
	v_pk_fma_f32 v[76:77], v[122:123], v[38:39], v[126:127]
	v_pk_fma_f32 v[74:75], v[124:125], v[40:41], v[128:129]
	v_pk_fma_f32 v[76:77], v[118:119], v[146:147], v[76:77]
	v_pk_fma_f32 v[74:75], v[120:121], v[144:145], v[74:75]
	v_pk_fma_f32 v[76:77], v[106:107], v[132:133], v[76:77]
	v_pk_fma_f32 v[132:133], v[112:113], v[36:37], v[116:117]
	v_pk_fma_f32 v[74:75], v[108:109], v[134:135], v[74:75]
	v_pk_fma_f32 v[132:133], v[104:105], v[140:141], v[132:133]
	v_mov_b64_e32 v[150:151], s[40:41]
	v_pk_fma_f32 v[68:69], v[100:101], v[68:69], v[132:133]
	v_pk_mul_f32 v[132:133], v[74:75], v[74:75]
	v_pk_fma_f32 v[134:135], v[110:111], v[34:35], v[114:115]
	v_pk_fma_f32 v[132:133], v[132:133], s[38:39], v[150:151] op_sel_hi:[1,0,0] neg_lo:[1,0,0] neg_hi:[1,0,0]
	v_pk_fma_f32 v[134:135], v[102:103], v[142:143], v[134:135]
	v_pk_mul_f32 v[132:133], v[74:75], v[132:133]
	v_pk_fma_f32 v[66:67], v[98:99], v[66:67], v[134:135]
	v_exp_f32_e32 v132, v132
	v_exp_f32_e32 v133, v133
	v_pk_mul_f32 v[134:135], v[76:77], v[76:77]
	v_pk_add_f32 v[132:133], v[132:133], 1.0 op_sel_hi:[1,0]
	s_nop 0
	v_rcp_f32_e32 v132, v132
	v_rcp_f32_e32 v133, v133
	s_nop 0
	v_pk_mul_f32 v[74:75], v[74:75], v[132:133]
	v_pk_fma_f32 v[132:133], v[134:135], s[38:39], v[150:151] op_sel_hi:[1,0,0] neg_lo:[1,0,0] neg_hi:[1,0,0]
	v_pk_mul_f32 v[68:69], v[68:69], v[74:75]
	v_pk_mul_f32 v[132:133], v[76:77], v[132:133]
	s_nop 0
	v_exp_f32_e32 v132, v132
	v_exp_f32_e32 v133, v133
	s_nop 0
	v_pk_add_f32 v[132:133], v[132:133], 1.0 op_sel_hi:[1,0]
	s_nop 0
	v_rcp_f32_e32 v132, v132
	v_rcp_f32_e32 v133, v133
	s_nop 0
	v_pk_mul_f32 v[76:77], v[76:77], v[132:133]
	s_nop 0
	v_pk_mul_f32 v[66:67], v[66:67], v[76:77]
	s_nop 0
	v_cvt_pk_f16_f32 v66, v66, v67
	v_cvt_pk_f16_f32 v67, v68, v69
	v_mad_i64_i32 v[68:69], s[16:17], v138, s86, v[240:241]
	global_store_dwordx2 v[68:69], v[66:67], off
; __device__ __forceinline__ unsigned pkh(float lo, float hi) { f32x2 v = {lo, hi}; h16x2 h = __builtin_convertvector(v, h16x2); return __builtin_bit_cast(unsigned, h); }
;     __device__ __forceinline__ void operator()(f32x4 (&acc)[2][2][4][2], const Unit& u, const Order& S, int wr, int wc, int fr_, int fq_, LAS unsigned char* xl, int ui) const {
;     ...
;                     h[0][bj] = __builtin_elementwise_fma(w0[bj], pm2, __builtin_elementwise_fma(w1[bj], pm1, __builtin_elementwise_fma(w2[bj], x0, bb[bj])));
;                     h[1][bj] = __builtin_elementwise_fma(w0[bj], pm1, __builtin_elementwise_fma(w1[bj], x0, __builtin_elementwise_fma(w2[bj], x1, bb[bj])));
;                     h[2][bj] = __builtin_elementwise_fma(w0[bj], x0, __builtin_elementwise_fma(w1[bj], x1, __builtin_elementwise_fma(w2[bj], x2, bb[bj])));
;                     h[3][bj] = __builtin_elementwise_fma(w0[bj], x1, __builtin_elementwise_fma(w1[bj], x2, __builtin_elementwise_fma(w2[bj], x3, bb[bj])));
;                 }
; #pragma unroll
;                 for (int m = 0; m < 4; ++m) {
;                     f32x4 o; { const f32x2 g0 = gelu_tanh2((f32x2){h[m][0][0], h[m][0][1]}) * (f32x2){h[m][1][0], h[m][1][1]}, g1 = gelu_tanh2((f32x2){h[m][0][2], h[m][0][3]}) * (f32x2){h[m][1][2], h[m][1][3]}; o = (f32x4){g0.x, g0.y, g1.x, g1.y}; }
;                     const int trow = trow0 + ai * HALF + m;
;                     if (trow >= lo) { u32x2 pk; pk.x = pkh(o[0], o[1]); pk.y = pkh(o[2], o[3]); *(u32x2*)(U + (size_t)(rs + trow) * FF + u.pn * HALF + tcol + 16 * n) = pk; }
.LBB0_518:
	s_or_b64 exec, exec, s[14:15]
	v_add_u32_e32 v66, 0x82, v215
	s_movk_i32 s14, 0xff7f
	v_cmp_lt_i32_e64 s[14:15], s14, v215
	v_add_u32_e32 v132, s43, v66
	s_and_saveexec_b64 s[16:17], s[14:15]
	s_cbranch_execz .LBB0_520
	v_pk_fma_f32 v[66:67], v[124:125], v[88:89], v[128:129]
	v_pk_fma_f32 v[76:77], v[110:111], v[82:83], v[114:115]
	v_pk_fma_f32 v[66:67], v[120:121], v[40:41], v[66:67]
	v_pk_fma_f32 v[76:77], v[102:103], v[34:35], v[76:77]
	v_pk_fma_f32 v[66:67], v[108:109], v[144:145], v[66:67]
	v_pk_fma_f32 v[76:77], v[98:99], v[142:143], v[76:77]
	v_pk_mul_f32 v[134:135], v[66:67], v[66:67]
	v_mov_b64_e32 v[142:143], s[40:41]
	v_pk_fma_f32 v[134:135], v[134:135], s[38:39], v[142:143] op_sel_hi:[1,0,0] neg_lo:[1,0,0] neg_hi:[1,0,0]
	v_pk_fma_f32 v[68:69], v[122:123], v[86:87], v[126:127]
	v_pk_mul_f32 v[134:135], v[66:67], v[134:135]
	v_pk_fma_f32 v[68:69], v[118:119], v[38:39], v[68:69]
	v_exp_f32_e32 v134, v134
	v_exp_f32_e32 v135, v135
	v_pk_fma_f32 v[74:75], v[112:113], v[84:85], v[116:117]
	v_pk_fma_f32 v[68:69], v[106:107], v[146:147], v[68:69]
	v_pk_fma_f32 v[74:75], v[104:105], v[36:37], v[74:75]
	v_pk_add_f32 v[134:135], v[134:135], 1.0 op_sel_hi:[1,0]
	v_pk_fma_f32 v[74:75], v[100:101], v[140:141], v[74:75]
	v_rcp_f32_e32 v134, v134
	v_rcp_f32_e32 v135, v135
	v_pk_mul_f32 v[140:141], v[68:69], v[68:69]
	v_pk_mul_f32 v[66:67], v[66:67], v[134:135]
	v_pk_fma_f32 v[134:135], v[140:141], s[38:39], v[142:143] op_sel_hi:[1,0,0] neg_lo:[1,0,0] neg_hi:[1,0,0]
	v_pk_mul_f32 v[66:67], v[74:75], v[66:67]
	v_pk_mul_f32 v[134:135], v[68:69], v[134:135]
	s_nop 0
	v_exp_f32_e32 v134, v134
	v_exp_f32_e32 v135, v135
	s_nop 0
	v_pk_add_f32 v[134:135], v[134:135], 1.0 op_sel_hi:[1,0]
	s_nop 0
	v_rcp_f32_e32 v134, v134
	v_rcp_f32_e32 v135, v135
	s_nop 0
	v_pk_mul_f32 v[68:69], v[68:69], v[134:135]
	s_nop 0
	v_pk_mul_f32 v[68:69], v[76:77], v[68:69]
	s_nop 0
	v_cvt_pk_f16_f32 v68, v68, v69
	v_cvt_pk_f16_f32 v69, v66, v67
	v_mad_i64_i32 v[66:67], s[50:51], v132, s86, v[240:241]
	global_store_dwordx2 v[66:67], v[68:69], off
.LBB0_520:
	s_or_b64 exec, exec, s[16:17]
	v_add_u32_e32 v66, 0x83, v215
	s_movk_i32 s16, 0xff7e
	v_cmp_lt_i32_e64 s[16:17], s16, v215
	v_add_u32_e32 v133, s43, v66
	s_and_saveexec_b64 s[50:51], s[16:17]
	s_cbranch_execz .LBB0_522
	v_pk_fma_f32 v[66:67], v[124:125], v[96:97], v[128:129]
	v_pk_fma_f32 v[68:69], v[122:123], v[94:95], v[126:127]
	v_pk_fma_f32 v[66:67], v[120:121], v[88:89], v[66:67]
	v_pk_fma_f32 v[68:69], v[118:119], v[86:87], v[68:69]
	v_pk_fma_f32 v[40:41], v[108:109], v[40:41], v[66:67]
	v_pk_fma_f32 v[38:39], v[106:107], v[38:39], v[68:69]
	v_pk_fma_f32 v[68:69], v[110:111], v[90:91], v[114:115]
	v_pk_mul_f32 v[74:75], v[40:41], v[40:41]
	v_pk_fma_f32 v[68:69], v[102:103], v[82:83], v[68:69]
	v_pk_mul_f32 v[76:77], v[38:39], v[38:39]
	v_mov_b64_e32 v[82:83], s[40:41]
	v_pk_fma_f32 v[74:75], v[74:75], s[38:39], v[82:83] op_sel_hi:[1,0,0] neg_lo:[1,0,0] neg_hi:[1,0,0]
	v_pk_fma_f32 v[76:77], v[76:77], s[38:39], v[82:83] op_sel_hi:[1,0,0] neg_lo:[1,0,0] neg_hi:[1,0,0]
	v_pk_mul_f32 v[74:75], v[40:41], v[74:75]
	v_pk_mul_f32 v[76:77], v[38:39], v[76:77]
	v_exp_f32_e32 v74, v74
	v_exp_f32_e32 v75, v75
	v_exp_f32_e32 v76, v76
	v_exp_f32_e32 v77, v77
	v_pk_fma_f32 v[66:67], v[112:113], v[92:93], v[116:117]
	v_pk_add_f32 v[74:75], v[74:75], 1.0 op_sel_hi:[1,0]
	v_pk_fma_f32 v[66:67], v[104:105], v[84:85], v[66:67]
	v_pk_add_f32 v[76:77], v[76:77], 1.0 op_sel_hi:[1,0]
	v_rcp_f32_e32 v74, v74
	v_rcp_f32_e32 v75, v75
	v_rcp_f32_e32 v76, v76
	v_rcp_f32_e32 v77, v77
	v_pk_fma_f32 v[36:37], v[100:101], v[36:37], v[66:67]
	v_pk_fma_f32 v[34:35], v[98:99], v[34:35], v[68:69]
	v_pk_mul_f32 v[40:41], v[40:41], v[74:75]
	v_pk_mul_f32 v[38:39], v[38:39], v[76:77]
	v_pk_mul_f32 v[36:37], v[36:37], v[40:41]
	v_pk_mul_f32 v[34:35], v[34:35], v[38:39]
	s_nop 0
	v_cvt_pk_f16_f32 v34, v34, v35
	v_cvt_pk_f16_f32 v35, v36, v37
	v_mad_i64_i32 v[36:37], s[92:93], v133, s86, v[240:241]
	global_store_dwordx2 v[36:37], v[34:35], off

; #define LAS __attribute__((address_space(3)))
; __device__ __forceinline__ unsigned pkh(float lo, float hi) { f32x2 v = {lo, hi}; h16x2 h = __builtin_convertvector(v, h16x2); return __builtin_bit_cast(unsigned, h); }
; __device__ __forceinline__ float dpp_shr1_keep(float keep, float v) { return __builtin_bit_cast(float, __builtin_amdgcn_update_dpp(__builtin_bit_cast(int, keep), __builtin_bit_cast(int, v), 0x111, 0xf, 0xf, false)); }
;     __device__ __forceinline__ void operator()(f32x4 (&acc)[2][2][4][2], const Unit& u, const Order& S, int wr, int wc, int fr_, int fq_, LAS unsigned char* xl, int ui) const {
;     ...
;                     if (g > 0) { r62 = *(const LAS f32x4*)(bnd + ((g - 1) * 2 + 0) * 256 + bj * HALF + tcol + 16 * n); r63 = *(const LAS f32x4*)(bnd + ((g - 1) * 2 + 1) * 256 + bj * HALF + tcol + 16 * n); }
;                     const f32x4 x0 = acc[ai][bj][0][n], x1 = acc[ai][bj][1][n], x2 = acc[ai][bj][2][n], x3 = acc[ai][bj][3][n];
;                     f32x4 pm1, pm2;
; #pragma unroll
;                     for (int e = 0; e < 4; ++e) { pm1[e] = dpp_shr1_keep(r63[e], x3[e]); pm2[e] = dpp_shr1_keep(r62[e], x2[e]); }
;                     h[0][bj] = __builtin_elementwise_fma(w0[bj], pm2, __builtin_elementwise_fma(w1[bj], pm1, __builtin_elementwise_fma(w2[bj], x0, bb[bj])));
;                     h[1][bj] = __builtin_elementwise_fma(w0[bj], pm1, __builtin_elementwise_fma(w1[bj], x0, __builtin_elementwise_fma(w2[bj], x1, bb[bj])));
;                     h[2][bj] = __builtin_elementwise_fma(w0[bj], x0, __builtin_elementwise_fma(w1[bj], x1, __builtin_elementwise_fma(w2[bj], x2, bb[bj])));
;                     h[3][bj] = __builtin_elementwise_fma(w0[bj], x1, __builtin_elementwise_fma(w1[bj], x2, __builtin_elementwise_fma(w2[bj], x3, bb[bj])));
;                 }
; #pragma unroll
;                 for (int m = 0; m < 4; ++m) {
;                     f32x4 o; { const f32x2 g0 = gelu_tanh2((f32x2){h[m][0][0], h[m][0][1]}) * (f32x2){h[m][1][0], h[m][1][1]}, g1 = gelu_tanh2((f32x2){h[m][0][2], h[m][0][3]}) * (f32x2){h[m][1][2], h[m][1][3]}; o = (f32x4){g0.x, g0.y, g1.x, g1.y}; }
;                     const int trow = trow0 + ai * HALF + m;
;                     if (trow >= lo) { u32x2 pk; pk.x = pkh(o[0], o[1]); pk.y = pkh(o[2], o[3]); *(u32x2*)(U + (size_t)(rs + trow) * FF + u.pn * HALF + tcol + 16 * n) = pk; }
.LBB0_530:
	s_or_b64 exec, exec, s[2:3]
	v_mov_b32_e32 v131, v130
	v_mov_b32_e32 v42, v130
	v_mov_b32_e32 v43, v130
	v_pk_mul_f32 v[54:55], v[16:17], v[42:43]
	v_pk_mul_f32 v[56:57], v[14:15], v[130:131]
	ds_read_b128 v[14:17], v190 offset:3136
	v_pk_mul_f32 v[50:51], v[12:13], v[42:43]
	ds_read_b128 v[42:45], v190 offset:2112
	ds_read_b128 v[46:49], v190 offset:2624
	v_pk_mul_f32 v[52:53], v[10:11], v[130:131]
	ds_read_b128 v[10:13], v190 offset:3648
	s_waitcnt lgkmcnt(0)
	v_mov_b32_dpp v14, v30 row_shr:1 row_mask:0xf bank_mask:0xf
	v_mov_b32_dpp v42, v18 row_shr:1 row_mask:0xf bank_mask:0xf
	v_mov_b32_dpp v15, v31 row_shr:1 row_mask:0xf bank_mask:0xf
	v_mov_b32_dpp v43, v19 row_shr:1 row_mask:0xf bank_mask:0xf
	v_mov_b32_dpp v16, v32 row_shr:1 row_mask:0xf bank_mask:0xf
	v_mov_b32_dpp v44, v20 row_shr:1 row_mask:0xf bank_mask:0xf
	v_mov_b32_dpp v17, v33 row_shr:1 row_mask:0xf bank_mask:0xf
	v_mov_b32_dpp v45, v21 row_shr:1 row_mask:0xf bank_mask:0xf
	v_mov_b32_dpp v10, v26 row_shr:1 row_mask:0xf bank_mask:0xf
	v_mov_b32_dpp v46, v22 row_shr:1 row_mask:0xf bank_mask:0xf
	v_mov_b32_dpp v11, v27 row_shr:1 row_mask:0xf bank_mask:0xf
	v_mov_b32_dpp v47, v23 row_shr:1 row_mask:0xf bank_mask:0xf
	v_mov_b32_dpp v12, v28 row_shr:1 row_mask:0xf bank_mask:0xf
	v_mov_b32_dpp v48, v24 row_shr:1 row_mask:0xf bank_mask:0xf
	v_mov_b32_dpp v13, v29 row_shr:1 row_mask:0xf bank_mask:0xf
	v_mov_b32_dpp v49, v25 row_shr:1 row_mask:0xf bank_mask:0xf
	s_and_saveexec_b64 s[2:3], s[10:11]
	s_cbranch_execz .LBB0_532
	v_pk_fma_f32 v[58:59], v[92:93], v[54:55], v[96:97]
	v_mov_b64_e32 v[62:63], s[40:41]
	v_pk_fma_f32 v[58:59], v[88:89], v[16:17], v[58:59]
	v_pk_fma_f32 v[60:61], v[90:91], v[56:57], v[94:95]
	v_pk_fma_f32 v[44:45], v[68:69], v[44:45], v[58:59]
	v_pk_fma_f32 v[58:59], v[76:77], v[50:51], v[84:85]
	v_pk_fma_f32 v[60:61], v[86:87], v[14:15], v[60:61]
	v_pk_fma_f32 v[58:59], v[40:41], v[12:13], v[58:59]
	v_pk_fma_f32 v[42:43], v[66:67], v[42:43], v[60:61]
	v_pk_fma_f32 v[48:49], v[36:37], v[48:49], v[58:59]
	v_pk_mul_f32 v[58:59], v[44:45], v[44:45]
	v_pk_fma_f32 v[60:61], v[74:75], v[52:53], v[82:83]
	v_pk_fma_f32 v[58:59], v[58:59], s[38:39], v[62:63] op_sel_hi:[1,0,0] neg_lo:[1,0,0] neg_hi:[1,0,0]
	v_pk_fma_f32 v[60:61], v[38:39], v[10:11], v[60:61]
	v_pk_mul_f32 v[58:59], v[44:45], v[58:59]
	v_pk_fma_f32 v[46:47], v[34:35], v[46:47], v[60:61]
	v_exp_f32_e32 v58, v58
	v_exp_f32_e32 v59, v59
	v_pk_mul_f32 v[60:61], v[42:43], v[42:43]
	v_pk_add_f32 v[58:59], v[58:59], 1.0 op_sel_hi:[1,0]
	s_nop 0
	v_rcp_f32_e32 v58, v58
	v_rcp_f32_e32 v59, v59
	s_nop 0
	v_pk_mul_f32 v[44:45], v[44:45], v[58:59]
	v_pk_fma_f32 v[58:59], v[60:61], s[38:39], v[62:63] op_sel_hi:[1,0,0] neg_lo:[1,0,0] neg_hi:[1,0,0]
	v_pk_mul_f32 v[44:45], v[48:49], v[44:45]
	v_pk_mul_f32 v[58:59], v[42:43], v[58:59]
	s_nop 0
	v_exp_f32_e32 v58, v58
	v_exp_f32_e32 v59, v59
	s_nop 0
	v_pk_add_f32 v[58:59], v[58:59], 1.0 op_sel_hi:[1,0]
	s_nop 0
	v_rcp_f32_e32 v58, v58
	v_rcp_f32_e32 v59, v59
	s_nop 0
	v_pk_mul_f32 v[42:43], v[42:43], v[58:59]
	s_nop 0
	v_pk_mul_f32 v[42:43], v[46:47], v[42:43]
	s_nop 0
	v_cvt_pk_f16_f32 v42, v42, v43
	v_cvt_pk_f16_f32 v43, v44, v45
	v_mad_i64_i32 v[44:45], s[4:5], v148, s86, v[240:241]
	global_store_dwordx2 v[44:45], v[42:43], off offset:32

; __device__ __forceinline__ unsigned pkh(float lo, float hi) { f32x2 v = {lo, hi}; h16x2 h = __builtin_convertvector(v, h16x2); return __builtin_bit_cast(unsigned, h); }
;     __device__ __forceinline__ void operator()(f32x4 (&acc)[2][2][4][2], const Unit& u, const Order& S, int wr, int wc, int fr_, int fq_, LAS unsigned char* xl, int ui) const {
;     ...
;                     h[0][bj] = __builtin_elementwise_fma(w0[bj], pm2, __builtin_elementwise_fma(w1[bj], pm1, __builtin_elementwise_fma(w2[bj], x0, bb[bj])));
;                     h[1][bj] = __builtin_elementwise_fma(w0[bj], pm1, __builtin_elementwise_fma(w1[bj], x0, __builtin_elementwise_fma(w2[bj], x1, bb[bj])));
;                     h[2][bj] = __builtin_elementwise_fma(w0[bj], x0, __builtin_elementwise_fma(w1[bj], x1, __builtin_elementwise_fma(w2[bj], x2, bb[bj])));
;                     h[3][bj] = __builtin_elementwise_fma(w0[bj], x1, __builtin_elementwise_fma(w1[bj], x2, __builtin_elementwise_fma(w2[bj], x3, bb[bj])));
;                 }
; #pragma unroll
;                 for (int m = 0; m < 4; ++m) {
;                     f32x4 o; { const f32x2 g0 = gelu_tanh2((f32x2){h[m][0][0], h[m][0][1]}) * (f32x2){h[m][1][0], h[m][1][1]}, g1 = gelu_tanh2((f32x2){h[m][0][2], h[m][0][3]}) * (f32x2){h[m][1][2], h[m][1][3]}; o = (f32x4){g0.x, g0.y, g1.x, g1.y}; }
;                     const int trow = trow0 + ai * HALF + m;
;                     if (trow >= lo) { u32x2 pk; pk.x = pkh(o[0], o[1]); pk.y = pkh(o[2], o[3]); *(u32x2*)(U + (size_t)(rs + trow) * FF + u.pn * HALF + tcol + 16 * n) = pk; }
.LBB0_536:
	v_pk_fma_f32 v[114:115], v[92:93], v[64:65], v[96:97]
	v_mov_b64_e32 v[118:119], s[40:41]
	v_pk_fma_f32 v[114:115], v[88:89], v[100:101], v[114:115]
	v_pk_fma_f32 v[116:117], v[90:91], v[62:63], v[94:95]
	v_pk_fma_f32 v[108:109], v[68:69], v[108:109], v[114:115]
	v_pk_fma_f32 v[114:115], v[76:77], v[72:73], v[84:85]
	v_pk_fma_f32 v[116:117], v[86:87], v[98:99], v[116:117]
	v_pk_fma_f32 v[114:115], v[40:41], v[104:105], v[114:115]
	v_pk_fma_f32 v[106:107], v[66:67], v[106:107], v[116:117]
	v_pk_fma_f32 v[112:113], v[36:37], v[112:113], v[114:115]
	v_pk_mul_f32 v[114:115], v[108:109], v[108:109]
	v_pk_fma_f32 v[116:117], v[74:75], v[70:71], v[82:83]
	v_pk_fma_f32 v[114:115], v[114:115], s[38:39], v[118:119] op_sel_hi:[1,0,0] neg_lo:[1,0,0] neg_hi:[1,0,0]
	v_pk_fma_f32 v[116:117], v[38:39], v[102:103], v[116:117]
	v_pk_mul_f32 v[114:115], v[108:109], v[114:115]
	v_pk_fma_f32 v[110:111], v[34:35], v[110:111], v[116:117]
	v_exp_f32_e32 v114, v114
	v_exp_f32_e32 v115, v115
	v_pk_mul_f32 v[116:117], v[106:107], v[106:107]
	v_pk_add_f32 v[114:115], v[114:115], 1.0 op_sel_hi:[1,0]
	s_nop 0
	v_rcp_f32_e32 v114, v114
	v_rcp_f32_e32 v115, v115
	s_nop 0
	v_pk_mul_f32 v[108:109], v[108:109], v[114:115]
	v_pk_fma_f32 v[114:115], v[116:117], s[38:39], v[118:119] op_sel_hi:[1,0,0] neg_lo:[1,0,0] neg_hi:[1,0,0]
	v_pk_mul_f32 v[108:109], v[108:109], v[112:113]
	v_pk_mul_f32 v[114:115], v[106:107], v[114:115]
	s_nop 0
	v_exp_f32_e32 v114, v114
	v_exp_f32_e32 v115, v115
	s_nop 0
	v_pk_add_f32 v[114:115], v[114:115], 1.0 op_sel_hi:[1,0]
	s_nop 0
	v_rcp_f32_e32 v114, v114
	v_rcp_f32_e32 v115, v115
	s_nop 0
	v_pk_mul_f32 v[106:107], v[106:107], v[114:115]
	s_nop 0
	v_pk_mul_f32 v[106:107], v[106:107], v[110:111]
	s_nop 0
	v_cvt_pk_f16_f32 v106, v106, v107
	v_cvt_pk_f16_f32 v107, v108, v109
	v_mad_i64_i32 v[108:109], s[8:9], v216, s86, v[240:241]
	global_store_dwordx2 v[108:109], v[106:107], off offset:32
	s_or_b64 exec, exec, s[2:3]
	s_and_saveexec_b64 s[2:3], s[4:5]
	s_cbranch_execz .LBB0_528
.LBB0_537:
	v_pk_fma_f32 v[106:107], v[76:77], v[80:81], v[84:85]
	v_mov_b64_e32 v[110:111], s[40:41]
	v_pk_fma_f32 v[106:107], v[40:41], v[72:73], v[106:107]
	v_pk_fma_f32 v[108:109], v[74:75], v[78:79], v[82:83]
	v_pk_fma_f32 v[104:105], v[36:37], v[104:105], v[106:107]
	v_pk_fma_f32 v[106:107], v[92:93], v[60:61], v[96:97]
	v_pk_fma_f32 v[108:109], v[38:39], v[70:71], v[108:109]
	v_pk_fma_f32 v[106:107], v[88:89], v[64:65], v[106:107]
	v_pk_fma_f32 v[102:103], v[34:35], v[102:103], v[108:109]
	v_pk_fma_f32 v[100:101], v[68:69], v[100:101], v[106:107]
	v_pk_fma_f32 v[108:109], v[90:91], v[58:59], v[94:95]
	v_pk_mul_f32 v[106:107], v[100:101], v[100:101]
	v_pk_fma_f32 v[108:109], v[86:87], v[62:63], v[108:109]
	v_pk_fma_f32 v[106:107], v[106:107], s[38:39], v[110:111] op_sel_hi:[1,0,0] neg_lo:[1,0,0] neg_hi:[1,0,0]
	v_pk_fma_f32 v[98:99], v[66:67], v[98:99], v[108:109]
	v_pk_mul_f32 v[106:107], v[100:101], v[106:107]
	v_pk_mul_f32 v[108:109], v[98:99], v[98:99]
	v_exp_f32_e32 v106, v106
	v_exp_f32_e32 v107, v107
	s_nop 0
	v_pk_add_f32 v[106:107], v[106:107], 1.0 op_sel_hi:[1,0]
	s_nop 0
	v_rcp_f32_e32 v106, v106
	v_rcp_f32_e32 v107, v107
	s_nop 0
	v_pk_mul_f32 v[100:101], v[100:101], v[106:107]
	v_pk_fma_f32 v[106:107], v[108:109], s[38:39], v[110:111] op_sel_hi:[1,0,0] neg_lo:[1,0,0] neg_hi:[1,0,0]
	v_pk_mul_f32 v[100:101], v[100:101], v[104:105]
	v_pk_mul_f32 v[106:107], v[98:99], v[106:107]
	s_nop 0
	v_exp_f32_e32 v106, v106
	v_exp_f32_e32 v107, v107
	s_nop 0
	v_pk_add_f32 v[106:107], v[106:107], 1.0 op_sel_hi:[1,0]
	s_nop 0
	v_rcp_f32_e32 v106, v106
	v_rcp_f32_e32 v107, v107
	s_nop 0
	v_pk_mul_f32 v[98:99], v[98:99], v[106:107]
	s_nop 0
	v_pk_mul_f32 v[98:99], v[98:99], v[102:103]
	s_nop 0
	v_cvt_pk_f16_f32 v98, v98, v99
	v_cvt_pk_f16_f32 v99, v100, v101
	v_mad_i64_i32 v[100:101], s[4:5], v174, s86, v[240:241]
	global_store_dwordx2 v[100:101], v[98:99], off offset:32
	s_or_b64 exec, exec, s[2:3]
	s_and_saveexec_b64 s[2:3], s[6:7]
	s_cbranch_execnz .LBB0_529
	s_branch .LBB0_530
; __device__ __forceinline__ unsigned pkh(float lo, float hi) { f32x2 v = {lo, hi}; h16x2 h = __builtin_convertvector(v, h16x2); return __builtin_bit_cast(unsigned, h); }
;     __device__ __forceinline__ void operator()(f32x4 (&acc)[2][2][4][2], const Unit& u, const Order& S, int wr, int wc, int fr_, int fq_, LAS unsigned char* xl, int ui) const {
;     ...
;                     h[0][bj] = __builtin_elementwise_fma(w0[bj], pm2, __builtin_elementwise_fma(w1[bj], pm1, __builtin_elementwise_fma(w2[bj], x0, bb[bj])));
;                     h[1][bj] = __builtin_elementwise_fma(w0[bj], pm1, __builtin_elementwise_fma(w1[bj], x0, __builtin_elementwise_fma(w2[bj], x1, bb[bj])));
;                     h[2][bj] = __builtin_elementwise_fma(w0[bj], x0, __builtin_elementwise_fma(w1[bj], x1, __builtin_elementwise_fma(w2[bj], x2, bb[bj])));
;                     h[3][bj] = __builtin_elementwise_fma(w0[bj], x1, __builtin_elementwise_fma(w1[bj], x2, __builtin_elementwise_fma(w2[bj], x3, bb[bj])));
;                 }
; #pragma unroll
;                 for (int m = 0; m < 4; ++m) {
;                     f32x4 o; { const f32x2 g0 = gelu_tanh2((f32x2){h[m][0][0], h[m][0][1]}) * (f32x2){h[m][1][0], h[m][1][1]}, g1 = gelu_tanh2((f32x2){h[m][0][2], h[m][0][3]}) * (f32x2){h[m][1][2], h[m][1][3]}; o = (f32x4){g0.x, g0.y, g1.x, g1.y}; }
;                     const int trow = trow0 + ai * HALF + m;
;                     if (trow >= lo) { u32x2 pk; pk.x = pkh(o[0], o[1]); pk.y = pkh(o[2], o[3]); *(u32x2*)(U + (size_t)(rs + trow) * FF + u.pn * HALF + tcol + 16 * n) = pk; }
.LBB0_538:
	v_pk_fma_f32 v[42:43], v[92:93], v[8:9], v[96:97]
	v_pk_fma_f32 v[44:45], v[90:91], v[6:7], v[94:95]
	v_pk_fma_f32 v[42:43], v[88:89], v[54:55], v[42:43]
	v_pk_fma_f32 v[44:45], v[86:87], v[56:57], v[44:45]
	v_pk_fma_f32 v[16:17], v[68:69], v[16:17], v[42:43]
	v_pk_fma_f32 v[14:15], v[66:67], v[14:15], v[44:45]
	v_pk_mul_f32 v[46:47], v[16:17], v[16:17]
	v_pk_mul_f32 v[48:49], v[14:15], v[14:15]
	v_mov_b64_e32 v[58:59], s[40:41]
	v_pk_fma_f32 v[46:47], v[46:47], s[38:39], v[58:59] op_sel_hi:[1,0,0] neg_lo:[1,0,0] neg_hi:[1,0,0]
	v_pk_fma_f32 v[48:49], v[48:49], s[38:39], v[58:59] op_sel_hi:[1,0,0] neg_lo:[1,0,0] neg_hi:[1,0,0]
	v_pk_mul_f32 v[46:47], v[16:17], v[46:47]
	v_pk_mul_f32 v[48:49], v[14:15], v[48:49]
	v_exp_f32_e32 v46, v46
	v_exp_f32_e32 v47, v47
	v_exp_f32_e32 v48, v48
	v_exp_f32_e32 v49, v49
	v_pk_fma_f32 v[42:43], v[76:77], v[4:5], v[84:85]
	v_pk_add_f32 v[46:47], v[46:47], 1.0 op_sel_hi:[1,0]
	v_pk_fma_f32 v[44:45], v[74:75], v[2:3], v[82:83]
	v_pk_add_f32 v[48:49], v[48:49], 1.0 op_sel_hi:[1,0]
	v_rcp_f32_e32 v46, v46
	v_rcp_f32_e32 v47, v47
	v_rcp_f32_e32 v48, v48
	v_rcp_f32_e32 v49, v49
	v_pk_fma_f32 v[42:43], v[40:41], v[50:51], v[42:43]
	v_pk_fma_f32 v[44:45], v[38:39], v[52:53], v[44:45]
	v_pk_fma_f32 v[12:13], v[36:37], v[12:13], v[42:43]
	v_pk_fma_f32 v[10:11], v[34:35], v[10:11], v[44:45]
	v_pk_mul_f32 v[16:17], v[16:17], v[46:47]
	v_pk_mul_f32 v[14:15], v[14:15], v[48:49]
	v_pk_mul_f32 v[12:13], v[12:13], v[16:17]
	v_pk_mul_f32 v[10:11], v[10:11], v[14:15]
	s_nop 0
	v_cvt_pk_f16_f32 v10, v10, v11
	v_cvt_pk_f16_f32 v11, v12, v13
	v_mad_i64_i32 v[12:13], s[4:5], v138, s86, v[240:241]
	global_store_dwordx2 v[12:13], v[10:11], off offset:32
	s_or_b64 exec, exec, s[2:3]
	s_and_saveexec_b64 s[2:3], s[14:15]
	s_cbranch_execz .LBB0_534
.LBB0_539:
	v_pk_fma_f32 v[10:11], v[92:93], v[20:21], v[96:97]
	v_pk_fma_f32 v[12:13], v[90:91], v[18:19], v[94:95]
	v_pk_fma_f32 v[10:11], v[88:89], v[8:9], v[10:11]
	v_pk_fma_f32 v[12:13], v[86:87], v[6:7], v[12:13]
	v_pk_fma_f32 v[10:11], v[68:69], v[54:55], v[10:11]
	v_pk_fma_f32 v[12:13], v[66:67], v[56:57], v[12:13]
	v_pk_mul_f32 v[42:43], v[10:11], v[10:11]
	v_pk_mul_f32 v[44:45], v[12:13], v[12:13]
	v_mov_b64_e32 v[46:47], s[40:41]
	v_pk_fma_f32 v[42:43], v[42:43], s[38:39], v[46:47] op_sel_hi:[1,0,0] neg_lo:[1,0,0] neg_hi:[1,0,0]
	v_pk_fma_f32 v[44:45], v[44:45], s[38:39], v[46:47] op_sel_hi:[1,0,0] neg_lo:[1,0,0] neg_hi:[1,0,0]
	v_pk_mul_f32 v[42:43], v[10:11], v[42:43]
	v_pk_mul_f32 v[44:45], v[12:13], v[44:45]
	v_exp_f32_e32 v42, v42
	v_exp_f32_e32 v43, v43
	v_exp_f32_e32 v44, v44
	v_exp_f32_e32 v45, v45
	v_pk_fma_f32 v[14:15], v[76:77], v[24:25], v[84:85]
	v_pk_add_f32 v[42:43], v[42:43], 1.0 op_sel_hi:[1,0]
	v_pk_fma_f32 v[16:17], v[74:75], v[22:23], v[82:83]
	v_pk_add_f32 v[44:45], v[44:45], 1.0 op_sel_hi:[1,0]
	v_rcp_f32_e32 v42, v42
	v_rcp_f32_e32 v43, v43
	v_rcp_f32_e32 v44, v44
	v_rcp_f32_e32 v45, v45
	v_pk_fma_f32 v[14:15], v[40:41], v[4:5], v[14:15]
	v_pk_fma_f32 v[16:17], v[38:39], v[2:3], v[16:17]
	v_pk_fma_f32 v[14:15], v[36:37], v[50:51], v[14:15]
	v_pk_fma_f32 v[16:17], v[34:35], v[52:53], v[16:17]
	v_pk_mul_f32 v[10:11], v[10:11], v[42:43]
	v_pk_mul_f32 v[12:13], v[12:13], v[44:45]
	v_pk_mul_f32 v[10:11], v[14:15], v[10:11]
	v_pk_mul_f32 v[12:13], v[16:17], v[12:13]
	s_nop 0
	v_cvt_pk_f16_f32 v12, v12, v13
	v_cvt_pk_f16_f32 v13, v10, v11
	v_mad_i64_i32 v[10:11], s[4:5], v132, s86, v[240:241]
	global_store_dwordx2 v[10:11], v[12:13], off offset:32
	s_or_b64 exec, exec, s[2:3]
	s_and_saveexec_b64 s[2:3], s[16:17]
	s_cbranch_execz .LBB0_535
.LBB0_540:
	v_pk_fma_f32 v[10:11], v[92:93], v[32:33], v[96:97]
	v_pk_fma_f32 v[12:13], v[90:91], v[30:31], v[94:95]
	v_pk_fma_f32 v[10:11], v[88:89], v[20:21], v[10:11]
	v_pk_fma_f32 v[12:13], v[86:87], v[18:19], v[12:13]
	v_pk_fma_f32 v[8:9], v[68:69], v[8:9], v[10:11]
	v_pk_fma_f32 v[6:7], v[66:67], v[6:7], v[12:13]
	v_pk_mul_f32 v[14:15], v[8:9], v[8:9]
	v_pk_mul_f32 v[16:17], v[6:7], v[6:7]
	v_mov_b64_e32 v[18:19], s[40:41]
	v_pk_fma_f32 v[14:15], v[14:15], s[38:39], v[18:19] op_sel_hi:[1,0,0] neg_lo:[1,0,0] neg_hi:[1,0,0]
	v_pk_fma_f32 v[16:17], v[16:17], s[38:39], v[18:19] op_sel_hi:[1,0,0] neg_lo:[1,0,0] neg_hi:[1,0,0]
	v_pk_mul_f32 v[14:15], v[8:9], v[14:15]
	v_pk_mul_f32 v[16:17], v[6:7], v[16:17]
	v_exp_f32_e32 v14, v14
	v_exp_f32_e32 v15, v15
	v_exp_f32_e32 v16, v16
	v_exp_f32_e32 v17, v17
	v_pk_fma_f32 v[10:11], v[76:77], v[28:29], v[84:85]
	v_pk_add_f32 v[14:15], v[14:15], 1.0 op_sel_hi:[1,0]
	v_pk_fma_f32 v[12:13], v[74:75], v[26:27], v[82:83]
	v_pk_add_f32 v[16:17], v[16:17], 1.0 op_sel_hi:[1,0]
	v_rcp_f32_e32 v14, v14
	v_rcp_f32_e32 v15, v15
	v_rcp_f32_e32 v16, v16
	v_rcp_f32_e32 v17, v17
	v_pk_fma_f32 v[10:11], v[40:41], v[24:25], v[10:11]
	v_pk_fma_f32 v[12:13], v[38:39], v[22:23], v[12:13]
	v_pk_fma_f32 v[4:5], v[36:37], v[4:5], v[10:11]
	v_pk_fma_f32 v[2:3], v[34:35], v[2:3], v[12:13]
	v_pk_mul_f32 v[8:9], v[8:9], v[14:15]
	v_pk_mul_f32 v[6:7], v[6:7], v[16:17]
	v_pk_mul_f32 v[4:5], v[4:5], v[8:9]
	v_pk_mul_f32 v[2:3], v[2:3], v[6:7]
	s_nop 0
	v_cvt_pk_f16_f32 v2, v2, v3
	v_cvt_pk_f16_f32 v3, v4, v5
	v_mad_i64_i32 v[4:5], s[4:5], v133, s86, v[240:241]
	global_store_dwordx2 v[4:5], v[2:3], off offset:32
	s_or_b64 exec, exec, s[2:3]
	s_andn2_b64 vcc, exec, s[0:1]
	s_mov_b64 s[0:1], -1
	s_cbranch_vccnz .LBB0_479

; __device__ __forceinline__ unsigned pkh(float lo, float hi) { f32x2 v = {lo, hi}; h16x2 h = __builtin_convertvector(v, h16x2); return __builtin_bit_cast(unsigned, h); }
; __device__ __forceinline__ float dpp_shr1_keep(float keep, float v) { return __builtin_bit_cast(float, __builtin_amdgcn_update_dpp(__builtin_bit_cast(int, keep), __builtin_bit_cast(int, v), 0x111, 0xf, 0xf, false)); }
;     __device__ __forceinline__ void operator()(f32x4 (&acc)[2][2][4][2], const Unit& u, const Order& S, int wr, int wc, int fr_, int fq_, LAS unsigned char* xl, int ui) const {
;     ...
;                     for (int e = 0; e < 4; ++e) { pm1[e] = dpp_shr1_keep(r63[e], x3[e]); pm2[e] = dpp_shr1_keep(r62[e], x2[e]); }
;                     h[0][bj] = __builtin_elementwise_fma(w0[bj], pm2, __builtin_elementwise_fma(w1[bj], pm1, __builtin_elementwise_fma(w2[bj], x0, bb[bj])));
;                     h[1][bj] = __builtin_elementwise_fma(w0[bj], pm1, __builtin_elementwise_fma(w1[bj], x0, __builtin_elementwise_fma(w2[bj], x1, bb[bj])));
;                     h[2][bj] = __builtin_elementwise_fma(w0[bj], x0, __builtin_elementwise_fma(w1[bj], x1, __builtin_elementwise_fma(w2[bj], x2, bb[bj])));
;                     h[3][bj] = __builtin_elementwise_fma(w0[bj], x1, __builtin_elementwise_fma(w1[bj], x2, __builtin_elementwise_fma(w2[bj], x3, bb[bj])));
;                 }
; #pragma unroll
;                 for (int m = 0; m < 4; ++m) {
;                     f32x4 o; { const f32x2 g0 = gelu_tanh2((f32x2){h[m][0][0], h[m][0][1]}) * (f32x2){h[m][1][0], h[m][1][1]}, g1 = gelu_tanh2((f32x2){h[m][0][2], h[m][0][3]}) * (f32x2){h[m][1][2], h[m][1][3]}; o = (f32x4){g0.x, g0.y, g1.x, g1.y}; }
;                     const int trow = trow0 + ai * HALF + m;
;                     if (trow >= lo) { u32x2 pk; pk.x = pkh(o[0], o[1]); pk.y = pkh(o[2], o[3]); *(u32x2*)(U + (size_t)(rs + trow) * FF + u.pn * HALF + tcol + 16 * n) = pk; }
.LBB0_1429:
	s_lshl_b32 s52, s4, 7
	s_lshl_b32 s47, s14, 8
	s_ashr_i32 s53, s52, 31
	v_mov_b64_e32 v[240:241], s[58:59]
	v_lshl_add_u64 v[240:241], s[52:53], 1, v[240:241]
	v_lshl_add_u64 v[240:241], v[202:203], 1, v[240:241]
	s_waitcnt lgkmcnt(0)
	v_mov_b32_dpp v164, v144 row_shr:1 row_mask:0xf bank_mask:0xf
	v_mov_b32_dpp v176, v140 row_shr:1 row_mask:0xf bank_mask:0xf
	v_mov_b32_dpp v165, v145 row_shr:1 row_mask:0xf bank_mask:0xf
	v_mov_b32_dpp v177, v141 row_shr:1 row_mask:0xf bank_mask:0xf
	v_mov_b32_dpp v166, v146 row_shr:1 row_mask:0xf bank_mask:0xf
	v_mov_b32_dpp v178, v142 row_shr:1 row_mask:0xf bank_mask:0xf
	v_mov_b32_dpp v167, v147 row_shr:1 row_mask:0xf bank_mask:0xf
	v_mov_b32_dpp v179, v143 row_shr:1 row_mask:0xf bank_mask:0xf
	v_cmp_lt_i32_e64 s[4:5], 1, v212
	v_add_u32_e32 v213, s47, v212
	s_and_saveexec_b64 s[6:7], s[4:5]
	s_cbranch_execz .LBB0_1431
	v_pk_fma_f32 v[218:219], v[126:127], v[162:163], v[130:131]
	v_pk_fma_f32 v[220:221], v[124:125], v[160:161], v[128:129]
	v_pk_fma_f32 v[218:219], v[122:123], v[170:171], v[218:219]
	v_pk_fma_f32 v[220:221], v[120:121], v[168:169], v[220:221]
	v_pk_fma_f32 v[174:175], v[108:109], v[174:175], v[218:219]
	v_pk_fma_f32 v[172:173], v[106:107], v[172:173], v[220:221]
	v_pk_mul_f32 v[222:223], v[174:175], v[174:175]
	v_pk_mul_f32 v[224:225], v[172:173], v[172:173]
	v_mov_b64_e32 v[226:227], s[44:45]
	v_pk_fma_f32 v[222:223], v[222:223], s[42:43], v[226:227] op_sel_hi:[1,0,0] neg_lo:[1,0,0] neg_hi:[1,0,0]
	v_pk_fma_f32 v[224:225], v[224:225], s[42:43], v[226:227] op_sel_hi:[1,0,0] neg_lo:[1,0,0] neg_hi:[1,0,0]
	v_pk_mul_f32 v[222:223], v[174:175], v[222:223]
	v_pk_mul_f32 v[224:225], v[172:173], v[224:225]
	v_exp_f32_e32 v222, v222
	v_exp_f32_e32 v223, v223
	v_exp_f32_e32 v224, v224
	v_exp_f32_e32 v225, v225
	v_pk_fma_f32 v[218:219], v[112:113], v[158:159], v[118:119]
	v_pk_add_f32 v[222:223], v[222:223], 1.0 op_sel_hi:[1,0]
	v_pk_fma_f32 v[220:221], v[110:111], v[156:157], v[116:117]
	v_pk_add_f32 v[224:225], v[224:225], 1.0 op_sel_hi:[1,0]
	v_rcp_f32_e32 v222, v222
	v_rcp_f32_e32 v223, v223
	v_rcp_f32_e32 v224, v224
	v_rcp_f32_e32 v225, v225
	v_pk_fma_f32 v[218:219], v[104:105], v[166:167], v[218:219]
	v_pk_fma_f32 v[220:221], v[102:103], v[164:165], v[220:221]
	v_pk_fma_f32 v[178:179], v[100:101], v[178:179], v[218:219]
	v_pk_fma_f32 v[176:177], v[98:99], v[176:177], v[220:221]
	v_pk_mul_f32 v[174:175], v[174:175], v[222:223]
	v_pk_mul_f32 v[172:173], v[172:173], v[224:225]
	v_pk_mul_f32 v[174:175], v[174:175], v[178:179]
	v_pk_mul_f32 v[172:173], v[172:173], v[176:177]
	s_nop 0
	v_cvt_pk_f16_f32 v172, v172, v173
	v_cvt_pk_f16_f32 v173, v174, v175
	v_mad_i64_i32 v[174:175], s[8:9], v213, s84, v[240:241]
	global_store_dwordx2 v[174:175], v[172:173], off
.LBB0_1431:
	s_or_b64 exec, exec, s[6:7]
	v_or_b32_e32 v172, 1, v212
	v_cmp_lt_i32_e64 s[6:7], 0, v212
	v_add_u32_e32 v172, s47, v172
	s_and_saveexec_b64 s[8:9], s[6:7]
	s_cbranch_execz .LBB0_1433
	v_pk_fma_f32 v[178:179], v[126:127], v[154:155], v[130:131]
	v_pk_fma_f32 v[218:219], v[124:125], v[152:153], v[128:129]
	v_pk_fma_f32 v[178:179], v[122:123], v[162:163], v[178:179]
	v_pk_fma_f32 v[218:219], v[120:121], v[160:161], v[218:219]
	v_pk_fma_f32 v[170:171], v[108:109], v[170:171], v[178:179]
	v_pk_fma_f32 v[168:169], v[106:107], v[168:169], v[218:219]
	v_pk_mul_f32 v[178:179], v[170:171], v[170:171]
	v_pk_mul_f32 v[218:219], v[168:169], v[168:169]
	v_mov_b64_e32 v[220:221], s[44:45]
	v_pk_fma_f32 v[178:179], v[178:179], s[42:43], v[220:221] op_sel_hi:[1,0,0] neg_lo:[1,0,0] neg_hi:[1,0,0]
	v_pk_fma_f32 v[218:219], v[218:219], s[42:43], v[220:221] op_sel_hi:[1,0,0] neg_lo:[1,0,0] neg_hi:[1,0,0]
	v_pk_mul_f32 v[178:179], v[170:171], v[178:179]
	v_pk_mul_f32 v[218:219], v[168:169], v[218:219]
	v_exp_f32_e32 v178, v178
	v_exp_f32_e32 v179, v179
	v_exp_f32_e32 v218, v218
	v_exp_f32_e32 v219, v219
	v_pk_fma_f32 v[174:175], v[112:113], v[150:151], v[118:119]
	v_pk_add_f32 v[178:179], v[178:179], 1.0 op_sel_hi:[1,0]
	v_pk_fma_f32 v[176:177], v[110:111], v[148:149], v[116:117]
	v_pk_add_f32 v[218:219], v[218:219], 1.0 op_sel_hi:[1,0]
	v_rcp_f32_e32 v178, v178
	v_rcp_f32_e32 v179, v179
	v_rcp_f32_e32 v218, v218
	v_rcp_f32_e32 v219, v219
	v_pk_fma_f32 v[174:175], v[104:105], v[158:159], v[174:175]
	v_pk_fma_f32 v[176:177], v[102:103], v[156:157], v[176:177]
	v_pk_fma_f32 v[166:167], v[100:101], v[166:167], v[174:175]
	v_pk_fma_f32 v[164:165], v[98:99], v[164:165], v[176:177]
	v_pk_mul_f32 v[170:171], v[170:171], v[178:179]
	v_pk_mul_f32 v[168:169], v[168:169], v[218:219]
	v_pk_mul_f32 v[166:167], v[170:171], v[166:167]
	v_pk_mul_f32 v[164:165], v[168:169], v[164:165]
	s_nop 0
	v_cvt_pk_f16_f32 v164, v164, v165
	v_cvt_pk_f16_f32 v165, v166, v167
	v_mad_i64_i32 v[166:167], s[10:11], v172, s84, v[240:241]
	global_store_dwordx2 v[166:167], v[164:165], off
; #define LAS __attribute__((address_space(3)))
; __device__ __forceinline__ unsigned pkh(float lo, float hi) { f32x2 v = {lo, hi}; h16x2 h = __builtin_convertvector(v, h16x2); return __builtin_bit_cast(unsigned, h); }
;     __device__ __forceinline__ void operator()(f32x4 (&acc)[2][2][4][2], const Unit& u, const Order& S, int wr, int wc, int fr_, int fq_, LAS unsigned char* xl, int ui) const {
;     ...
;                 const float sc = __builtin_amdgcn_rsqf(ss4[m] * (1.0f / DM) + EPS);
; #pragma unroll
;                 for (int bj = 0; bj < 2; ++bj)
; #pragma unroll
;                     for (int n = 0; n < 2; ++n) acc[ai][bj][m][n] *= sc;
;     ...
;                     if (g > 0) { r62 = *(const LAS f32x4*)(bnd + ((g - 1) * 2 + 0) * 256 + bj * HALF + tcol + 16 * n); r63 = *(const LAS f32x4*)(bnd + ((g - 1) * 2 + 1) * 256 + bj * HALF + tcol + 16 * n); }
;                     const f32x4 x0 = acc[ai][bj][0][n], x1 = acc[ai][bj][1][n], x2 = acc[ai][bj][2][n], x3 = acc[ai][bj][3][n];
;                     f32x4 pm1, pm2;
; #pragma unroll
;                     for (int e = 0; e < 4; ++e) { pm1[e] = dpp_shr1_keep(r63[e], x3[e]); pm2[e] = dpp_shr1_keep(r62[e], x2[e]); }
;                     h[0][bj] = __builtin_elementwise_fma(w0[bj], pm2, __builtin_elementwise_fma(w1[bj], pm1, __builtin_elementwise_fma(w2[bj], x0, bb[bj])));
;                     h[1][bj] = __builtin_elementwise_fma(w0[bj], pm1, __builtin_elementwise_fma(w1[bj], x0, __builtin_elementwise_fma(w2[bj], x1, bb[bj])));
;                     h[2][bj] = __builtin_elementwise_fma(w0[bj], x0, __builtin_elementwise_fma(w1[bj], x1, __builtin_elementwise_fma(w2[bj], x2, bb[bj])));
;                     h[3][bj] = __builtin_elementwise_fma(w0[bj], x1, __builtin_elementwise_fma(w1[bj], x2, __builtin_elementwise_fma(w2[bj], x3, bb[bj])));
;                 }
; #pragma unroll
;                 for (int m = 0; m < 4; ++m) {
;                     f32x4 o; { const f32x2 g0 = gelu_tanh2((f32x2){h[m][0][0], h[m][0][1]}) * (f32x2){h[m][1][0], h[m][1][1]}, g1 = gelu_tanh2((f32x2){h[m][0][2], h[m][0][3]}) * (f32x2){h[m][1][2], h[m][1][3]}; o = (f32x4){g0.x, g0.y, g1.x, g1.y}; }
;                     const int trow = trow0 + ai * HALF + m;
;                     if (trow >= lo) { u32x2 pk; pk.x = pkh(o[0], o[1]); pk.y = pkh(o[2], o[3]); *(u32x2*)(U + (size_t)(rs + trow) * FF + u.pn * HALF + tcol + 16 * n) = pk; }
.LBB0_1433:
	s_or_b64 exec, exec, s[8:9]
	v_or_b32_e32 v164, 2, v212
	v_cmp_lt_i32_e64 s[8:9], -1, v212
	v_add_u32_e32 v164, s47, v164
	s_and_saveexec_b64 s[10:11], s[8:9]
	s_cbranch_execz .LBB0_1435
	v_pk_fma_f32 v[170:171], v[126:127], v[134:135], v[130:131]
	v_pk_fma_f32 v[174:175], v[124:125], v[132:133], v[128:129]
	v_pk_fma_f32 v[170:171], v[122:123], v[154:155], v[170:171]
	v_pk_fma_f32 v[174:175], v[120:121], v[152:153], v[174:175]
	v_pk_fma_f32 v[162:163], v[108:109], v[162:163], v[170:171]
	v_pk_fma_f32 v[160:161], v[106:107], v[160:161], v[174:175]
	v_pk_mul_f32 v[170:171], v[162:163], v[162:163]
	v_pk_mul_f32 v[174:175], v[160:161], v[160:161]
	v_mov_b64_e32 v[176:177], s[44:45]
	v_pk_fma_f32 v[170:171], v[170:171], s[42:43], v[176:177] op_sel_hi:[1,0,0] neg_lo:[1,0,0] neg_hi:[1,0,0]
	v_pk_fma_f32 v[174:175], v[174:175], s[42:43], v[176:177] op_sel_hi:[1,0,0] neg_lo:[1,0,0] neg_hi:[1,0,0]
	v_pk_mul_f32 v[170:171], v[162:163], v[170:171]
	v_pk_mul_f32 v[174:175], v[160:161], v[174:175]
	v_exp_f32_e32 v170, v170
	v_exp_f32_e32 v171, v171
	v_exp_f32_e32 v174, v174
	v_exp_f32_e32 v175, v175
	v_pk_fma_f32 v[166:167], v[112:113], v[142:143], v[118:119]
	v_pk_add_f32 v[170:171], v[170:171], 1.0 op_sel_hi:[1,0]
	v_pk_fma_f32 v[168:169], v[110:111], v[140:141], v[116:117]
	v_pk_add_f32 v[174:175], v[174:175], 1.0 op_sel_hi:[1,0]
	v_rcp_f32_e32 v170, v170
	v_rcp_f32_e32 v171, v171
	v_rcp_f32_e32 v174, v174
	v_rcp_f32_e32 v175, v175
	v_pk_fma_f32 v[166:167], v[104:105], v[150:151], v[166:167]
	v_pk_fma_f32 v[168:169], v[102:103], v[148:149], v[168:169]
	v_pk_fma_f32 v[158:159], v[100:101], v[158:159], v[166:167]
	v_pk_fma_f32 v[156:157], v[98:99], v[156:157], v[168:169]
	v_pk_mul_f32 v[162:163], v[162:163], v[170:171]
	v_pk_mul_f32 v[160:161], v[160:161], v[174:175]
	v_pk_mul_f32 v[158:159], v[158:159], v[162:163]
	v_pk_mul_f32 v[156:157], v[156:157], v[160:161]
	s_nop 0
	v_cvt_pk_f16_f32 v156, v156, v157
	v_cvt_pk_f16_f32 v157, v158, v159
	v_mad_i64_i32 v[158:159], s[12:13], v164, s84, v[240:241]
	global_store_dwordx2 v[158:159], v[156:157], off
.LBB0_1435:
	s_or_b64 exec, exec, s[10:11]
	v_or_b32_e32 v156, 3, v212
	v_add_u32_e32 v156, s47, v156
	s_and_saveexec_b64 s[10:11], s[8:9]
	s_cbranch_execz .LBB0_1437
	v_pk_fma_f32 v[138:139], v[126:127], v[138:139], v[130:131]
	v_pk_fma_f32 v[136:137], v[124:125], v[136:137], v[128:129]
	v_pk_fma_f32 v[134:135], v[122:123], v[134:135], v[138:139]
	v_pk_fma_f32 v[132:133], v[120:121], v[132:133], v[136:137]
	v_pk_fma_f32 v[144:145], v[110:111], v[144:145], v[116:117]
	v_pk_fma_f32 v[134:135], v[108:109], v[154:155], v[134:135]
	v_pk_fma_f32 v[132:133], v[106:107], v[152:153], v[132:133]
	v_pk_fma_f32 v[140:141], v[102:103], v[140:141], v[144:145]
	v_pk_mul_f32 v[136:137], v[134:135], v[134:135]
	v_pk_mul_f32 v[138:139], v[132:133], v[132:133]
	v_mov_b64_e32 v[144:145], s[44:45]
	v_pk_fma_f32 v[136:137], v[136:137], s[42:43], v[144:145] op_sel_hi:[1,0,0] neg_lo:[1,0,0] neg_hi:[1,0,0]
	v_pk_fma_f32 v[138:139], v[138:139], s[42:43], v[144:145] op_sel_hi:[1,0,0] neg_lo:[1,0,0] neg_hi:[1,0,0]
	v_pk_mul_f32 v[136:137], v[134:135], v[136:137]
	v_pk_mul_f32 v[138:139], v[132:133], v[138:139]
	v_exp_f32_e32 v136, v136
	v_exp_f32_e32 v137, v137
	v_exp_f32_e32 v138, v138
	v_exp_f32_e32 v139, v139
	v_pk_fma_f32 v[146:147], v[112:113], v[146:147], v[118:119]
	v_pk_add_f32 v[136:137], v[136:137], 1.0 op_sel_hi:[1,0]
	v_pk_fma_f32 v[142:143], v[104:105], v[142:143], v[146:147]
	v_pk_add_f32 v[138:139], v[138:139], 1.0 op_sel_hi:[1,0]
	v_rcp_f32_e32 v136, v136
	v_rcp_f32_e32 v137, v137
	v_rcp_f32_e32 v138, v138
	v_rcp_f32_e32 v139, v139
	v_pk_fma_f32 v[142:143], v[100:101], v[150:151], v[142:143]
	v_pk_fma_f32 v[140:141], v[98:99], v[148:149], v[140:141]
	v_pk_mul_f32 v[134:135], v[134:135], v[136:137]
	v_pk_mul_f32 v[132:133], v[132:133], v[138:139]
	v_pk_mul_f32 v[134:135], v[142:143], v[134:135]
	v_pk_mul_f32 v[132:133], v[140:141], v[132:133]
	s_nop 0
	v_cvt_pk_f16_f32 v132, v132, v133
	v_cvt_pk_f16_f32 v133, v134, v135
	v_mad_i64_i32 v[134:135], s[12:13], v156, s84, v[240:241]
	global_store_dwordx2 v[134:135], v[132:133], off
.LBB0_1437:
	s_or_b64 exec, exec, s[10:11]
	v_fmamk_f32 v114, v114, 0x3a800000, v211
	v_rsq_f32_e32 v114, v114
	ds_read_b128 v[132:135], v188 offset:3072
	ds_read_b128 v[136:139], v188 offset:2048
	v_add_u32_e32 v148, 0x80, v212
	v_pk_mul_f32 v[144:145], v[48:49], v[114:115] op_sel_hi:[1,0]
	v_pk_mul_f32 v[146:147], v[46:47], v[114:115] op_sel_hi:[1,0]
	v_pk_mul_f32 v[140:141], v[44:45], v[114:115] op_sel_hi:[1,0]
	v_pk_mul_f32 v[142:143], v[42:43], v[114:115] op_sel_hi:[1,0]
	ds_read_b128 v[42:45], v188 offset:3584
	ds_read_b128 v[46:49], v188 offset:2560
	s_waitcnt lgkmcnt(0)
	v_mov_b32_dpp v132, v94 row_shr:1 row_mask:0xf bank_mask:0xf
	v_mov_b32_dpp v136, v86 row_shr:1 row_mask:0xf bank_mask:0xf
	v_mov_b32_dpp v133, v95 row_shr:1 row_mask:0xf bank_mask:0xf
	v_mov_b32_dpp v137, v87 row_shr:1 row_mask:0xf bank_mask:0xf
	v_mov_b32_dpp v134, v96 row_shr:1 row_mask:0xf bank_mask:0xf
	v_mov_b32_dpp v138, v88 row_shr:1 row_mask:0xf bank_mask:0xf
	v_mov_b32_dpp v135, v97 row_shr:1 row_mask:0xf bank_mask:0xf
	v_mov_b32_dpp v139, v89 row_shr:1 row_mask:0xf bank_mask:0xf
	v_mov_b32_dpp v42, v90 row_shr:1 row_mask:0xf bank_mask:0xf
	v_mov_b32_dpp v46, v82 row_shr:1 row_mask:0xf bank_mask:0xf
	v_mov_b32_dpp v43, v91 row_shr:1 row_mask:0xf bank_mask:0xf
	v_mov_b32_dpp v47, v83 row_shr:1 row_mask:0xf bank_mask:0xf
	v_mov_b32_dpp v44, v92 row_shr:1 row_mask:0xf bank_mask:0xf
	v_mov_b32_dpp v48, v84 row_shr:1 row_mask:0xf bank_mask:0xf
	v_mov_b32_dpp v45, v93 row_shr:1 row_mask:0xf bank_mask:0xf
	v_mov_b32_dpp v49, v85 row_shr:1 row_mask:0xf bank_mask:0xf
	v_cmp_lt_i32_e64 s[10:11], s85, v212
	v_add_u32_e32 v148, s47, v148
	s_and_saveexec_b64 s[12:13], s[10:11]
	s_cbranch_execz .LBB0_1439
; __device__ __forceinline__ unsigned pkh(float lo, float hi) { f32x2 v = {lo, hi}; h16x2 h = __builtin_convertvector(v, h16x2); return __builtin_bit_cast(unsigned, h); }
;     __device__ __forceinline__ void operator()(f32x4 (&acc)[2][2][4][2], const Unit& u, const Order& S, int wr, int wc, int fr_, int fq_, LAS unsigned char* xl, int ui) const {
;     ...
;                 const float sc = __builtin_amdgcn_rsqf(ss4[m] * (1.0f / DM) + EPS);
; #pragma unroll
;                 for (int bj = 0; bj < 2; ++bj)
; #pragma unroll
;                     for (int n = 0; n < 2; ++n) acc[ai][bj][m][n] *= sc;
;     ...
;                     h[0][bj] = __builtin_elementwise_fma(w0[bj], pm2, __builtin_elementwise_fma(w1[bj], pm1, __builtin_elementwise_fma(w2[bj], x0, bb[bj])));
;                     h[1][bj] = __builtin_elementwise_fma(w0[bj], pm1, __builtin_elementwise_fma(w1[bj], x0, __builtin_elementwise_fma(w2[bj], x1, bb[bj])));
;                     h[2][bj] = __builtin_elementwise_fma(w0[bj], x0, __builtin_elementwise_fma(w1[bj], x1, __builtin_elementwise_fma(w2[bj], x2, bb[bj])));
;                     h[3][bj] = __builtin_elementwise_fma(w0[bj], x1, __builtin_elementwise_fma(w1[bj], x2, __builtin_elementwise_fma(w2[bj], x3, bb[bj])));
;                 }
; #pragma unroll
;                 for (int m = 0; m < 4; ++m) {
;                     f32x4 o; { const f32x2 g0 = gelu_tanh2((f32x2){h[m][0][0], h[m][0][1]}) * (f32x2){h[m][1][0], h[m][1][1]}, g1 = gelu_tanh2((f32x2){h[m][0][2], h[m][0][3]}) * (f32x2){h[m][1][2], h[m][1][3]}; o = (f32x4){g0.x, g0.y, g1.x, g1.y}; }
;                     const int trow = trow0 + ai * HALF + m;
;                     if (trow >= lo) { u32x2 pk; pk.x = pkh(o[0], o[1]); pk.y = pkh(o[2], o[3]); *(u32x2*)(U + (size_t)(rs + trow) * FF + u.pn * HALF + tcol + 16 * n) = pk; }
	v_pk_fma_f32 v[150:151], v[126:127], v[144:145], v[130:131]
	v_pk_fma_f32 v[152:153], v[124:125], v[146:147], v[128:129]
	v_pk_fma_f32 v[150:151], v[122:123], v[134:135], v[150:151]
	v_pk_fma_f32 v[152:153], v[120:121], v[132:133], v[152:153]
	v_pk_fma_f32 v[138:139], v[108:109], v[138:139], v[150:151]
	v_pk_fma_f32 v[136:137], v[106:107], v[136:137], v[152:153]
	v_pk_mul_f32 v[154:155], v[138:139], v[138:139]
	v_pk_mul_f32 v[158:159], v[136:137], v[136:137]
	v_mov_b64_e32 v[160:161], s[44:45]
	v_pk_fma_f32 v[154:155], v[154:155], s[42:43], v[160:161] op_sel_hi:[1,0,0] neg_lo:[1,0,0] neg_hi:[1,0,0]
	v_pk_fma_f32 v[158:159], v[158:159], s[42:43], v[160:161] op_sel_hi:[1,0,0] neg_lo:[1,0,0] neg_hi:[1,0,0]
	v_pk_mul_f32 v[154:155], v[138:139], v[154:155]
	v_pk_mul_f32 v[158:159], v[136:137], v[158:159]
	v_exp_f32_e32 v154, v154
	v_exp_f32_e32 v155, v155
	v_exp_f32_e32 v158, v158
	v_exp_f32_e32 v159, v159
	v_pk_fma_f32 v[150:151], v[112:113], v[140:141], v[118:119]
	v_pk_add_f32 v[154:155], v[154:155], 1.0 op_sel_hi:[1,0]
	v_pk_fma_f32 v[152:153], v[110:111], v[142:143], v[116:117]
	v_pk_add_f32 v[158:159], v[158:159], 1.0 op_sel_hi:[1,0]
	v_rcp_f32_e32 v154, v154
	v_rcp_f32_e32 v155, v155
	v_rcp_f32_e32 v158, v158
	v_rcp_f32_e32 v159, v159
	v_pk_fma_f32 v[150:151], v[104:105], v[44:45], v[150:151]
	v_pk_fma_f32 v[152:153], v[102:103], v[42:43], v[152:153]
	v_pk_fma_f32 v[48:49], v[100:101], v[48:49], v[150:151]
	v_pk_fma_f32 v[46:47], v[98:99], v[46:47], v[152:153]
	v_pk_mul_f32 v[138:139], v[138:139], v[154:155]
	v_pk_mul_f32 v[136:137], v[136:137], v[158:159]
	v_pk_mul_f32 v[48:49], v[48:49], v[138:139]
	v_pk_mul_f32 v[46:47], v[46:47], v[136:137]
	s_nop 0
	v_cvt_pk_f16_f32 v46, v46, v47
	v_cvt_pk_f16_f32 v47, v48, v49
	v_mad_i64_i32 v[48:49], s[14:15], v148, s84, v[240:241]
	global_store_dwordx2 v[48:49], v[46:47], off
.LBB0_1439:
	s_or_b64 exec, exec, s[12:13]
	v_fmamk_f32 v46, v115, 0x3a800000, v211
	v_rsq_f32_e32 v136, v46
	v_add_u32_e32 v46, 0x81, v212
	v_cmp_lt_i32_e64 s[12:13], s86, v212
	v_add_u32_e32 v138, s47, v46
	v_pk_mul_f32 v[40:41], v[40:41], v[136:137] op_sel_hi:[1,0]
	v_pk_mul_f32 v[38:39], v[38:39], v[136:137] op_sel_hi:[1,0]
	v_pk_mul_f32 v[36:37], v[36:37], v[136:137] op_sel_hi:[1,0]
	v_pk_mul_f32 v[34:35], v[34:35], v[136:137] op_sel_hi:[1,0]
	s_and_saveexec_b64 s[14:15], s[12:13]
	s_cbranch_execz .LBB0_1441
	v_pk_fma_f32 v[46:47], v[126:127], v[40:41], v[130:131]
	v_pk_fma_f32 v[48:49], v[124:125], v[38:39], v[128:129]
	v_pk_fma_f32 v[46:47], v[122:123], v[144:145], v[46:47]
	v_pk_fma_f32 v[48:49], v[120:121], v[146:147], v[48:49]
	v_pk_fma_f32 v[46:47], v[108:109], v[134:135], v[46:47]
	v_pk_fma_f32 v[48:49], v[106:107], v[132:133], v[48:49]
	v_pk_mul_f32 v[150:151], v[46:47], v[46:47]
	v_pk_mul_f32 v[152:153], v[48:49], v[48:49]
	v_mov_b64_e32 v[154:155], s[44:45]
	v_pk_fma_f32 v[150:151], v[150:151], s[42:43], v[154:155] op_sel_hi:[1,0,0] neg_lo:[1,0,0] neg_hi:[1,0,0]
	v_pk_fma_f32 v[152:153], v[152:153], s[42:43], v[154:155] op_sel_hi:[1,0,0] neg_lo:[1,0,0] neg_hi:[1,0,0]
	v_pk_mul_f32 v[150:151], v[46:47], v[150:151]
	v_pk_mul_f32 v[152:153], v[48:49], v[152:153]
	v_exp_f32_e32 v150, v150
	v_exp_f32_e32 v151, v151
	v_exp_f32_e32 v152, v152
	v_exp_f32_e32 v153, v153
	v_pk_fma_f32 v[132:133], v[112:113], v[36:37], v[118:119]
	v_pk_add_f32 v[150:151], v[150:151], 1.0 op_sel_hi:[1,0]
	v_pk_fma_f32 v[134:135], v[110:111], v[34:35], v[116:117]
	v_pk_add_f32 v[152:153], v[152:153], 1.0 op_sel_hi:[1,0]
	v_rcp_f32_e32 v150, v150
	v_rcp_f32_e32 v151, v151
	v_rcp_f32_e32 v152, v152
	v_rcp_f32_e32 v153, v153
	v_pk_fma_f32 v[132:133], v[104:105], v[140:141], v[132:133]
	v_pk_fma_f32 v[134:135], v[102:103], v[142:143], v[134:135]
	v_pk_fma_f32 v[44:45], v[100:101], v[44:45], v[132:133]
	v_pk_fma_f32 v[42:43], v[98:99], v[42:43], v[134:135]
	v_pk_mul_f32 v[46:47], v[46:47], v[150:151]
	v_pk_mul_f32 v[48:49], v[48:49], v[152:153]
	v_pk_mul_f32 v[44:45], v[44:45], v[46:47]
	v_pk_mul_f32 v[42:43], v[42:43], v[48:49]
	s_nop 0
	v_cvt_pk_f16_f32 v42, v42, v43
	v_cvt_pk_f16_f32 v43, v44, v45
	v_mad_i64_i32 v[44:45], s[16:17], v138, s84, v[240:241]
	global_store_dwordx2 v[44:45], v[42:43], off
; __device__ __forceinline__ unsigned pkh(float lo, float hi) { f32x2 v = {lo, hi}; h16x2 h = __builtin_convertvector(v, h16x2); return __builtin_bit_cast(unsigned, h); }
;     __device__ __forceinline__ void operator()(f32x4 (&acc)[2][2][4][2], const Unit& u, const Order& S, int wr, int wc, int fr_, int fq_, LAS unsigned char* xl, int ui) const {
;     ...
;                     h[0][bj] = __builtin_elementwise_fma(w0[bj], pm2, __builtin_elementwise_fma(w1[bj], pm1, __builtin_elementwise_fma(w2[bj], x0, bb[bj])));
;                     h[1][bj] = __builtin_elementwise_fma(w0[bj], pm1, __builtin_elementwise_fma(w1[bj], x0, __builtin_elementwise_fma(w2[bj], x1, bb[bj])));
;                     h[2][bj] = __builtin_elementwise_fma(w0[bj], x0, __builtin_elementwise_fma(w1[bj], x1, __builtin_elementwise_fma(w2[bj], x2, bb[bj])));
;                     h[3][bj] = __builtin_elementwise_fma(w0[bj], x1, __builtin_elementwise_fma(w1[bj], x2, __builtin_elementwise_fma(w2[bj], x3, bb[bj])));
;                 }
; #pragma unroll
;                 for (int m = 0; m < 4; ++m) {
;                     f32x4 o; { const f32x2 g0 = gelu_tanh2((f32x2){h[m][0][0], h[m][0][1]}) * (f32x2){h[m][1][0], h[m][1][1]}, g1 = gelu_tanh2((f32x2){h[m][0][2], h[m][0][3]}) * (f32x2){h[m][1][2], h[m][1][3]}; o = (f32x4){g0.x, g0.y, g1.x, g1.y}; }
;                     const int trow = trow0 + ai * HALF + m;
;                     if (trow >= lo) { u32x2 pk; pk.x = pkh(o[0], o[1]); pk.y = pkh(o[2], o[3]); *(u32x2*)(U + (size_t)(rs + trow) * FF + u.pn * HALF + tcol + 16 * n) = pk; }
.LBB0_1441:
	s_or_b64 exec, exec, s[14:15]
	v_add_u32_e32 v42, 0x82, v212
	v_cmp_lt_i32_e64 s[14:15], s87, v212
	v_add_u32_e32 v132, s47, v42
	s_and_saveexec_b64 s[16:17], s[14:15]
	s_cbranch_execz .LBB0_1443
	v_pk_fma_f32 v[42:43], v[126:127], v[88:89], v[130:131]
	v_pk_fma_f32 v[44:45], v[124:125], v[86:87], v[128:129]
	v_pk_fma_f32 v[42:43], v[122:123], v[40:41], v[42:43]
	v_pk_fma_f32 v[44:45], v[120:121], v[38:39], v[44:45]
	v_pk_fma_f32 v[42:43], v[108:109], v[144:145], v[42:43]
	v_pk_fma_f32 v[44:45], v[106:107], v[146:147], v[44:45]
	v_pk_mul_f32 v[134:135], v[42:43], v[42:43]
	v_pk_mul_f32 v[144:145], v[44:45], v[44:45]
	v_mov_b64_e32 v[146:147], s[44:45]
	v_pk_fma_f32 v[134:135], v[134:135], s[42:43], v[146:147] op_sel_hi:[1,0,0] neg_lo:[1,0,0] neg_hi:[1,0,0]
	v_pk_fma_f32 v[144:145], v[144:145], s[42:43], v[146:147] op_sel_hi:[1,0,0] neg_lo:[1,0,0] neg_hi:[1,0,0]
	v_pk_mul_f32 v[134:135], v[42:43], v[134:135]
	v_pk_mul_f32 v[144:145], v[44:45], v[144:145]
	v_exp_f32_e32 v134, v134
	v_exp_f32_e32 v135, v135
	v_exp_f32_e32 v144, v144
	v_exp_f32_e32 v145, v145
	v_pk_fma_f32 v[46:47], v[112:113], v[84:85], v[118:119]
	v_pk_add_f32 v[134:135], v[134:135], 1.0 op_sel_hi:[1,0]
	v_pk_fma_f32 v[48:49], v[110:111], v[82:83], v[116:117]
	v_pk_add_f32 v[144:145], v[144:145], 1.0 op_sel_hi:[1,0]
	v_rcp_f32_e32 v134, v134
	v_rcp_f32_e32 v135, v135
	v_rcp_f32_e32 v144, v144
	v_rcp_f32_e32 v145, v145
	v_pk_fma_f32 v[46:47], v[104:105], v[36:37], v[46:47]
	v_pk_fma_f32 v[48:49], v[102:103], v[34:35], v[48:49]
	v_pk_fma_f32 v[46:47], v[100:101], v[140:141], v[46:47]
	v_pk_fma_f32 v[48:49], v[98:99], v[142:143], v[48:49]
	v_pk_mul_f32 v[42:43], v[42:43], v[134:135]
	v_pk_mul_f32 v[44:45], v[44:45], v[144:145]
	v_pk_mul_f32 v[42:43], v[46:47], v[42:43]
	v_pk_mul_f32 v[44:45], v[48:49], v[44:45]
	s_nop 0
	v_cvt_pk_f16_f32 v44, v44, v45
	v_cvt_pk_f16_f32 v45, v42, v43
	v_mad_i64_i32 v[42:43], s[54:55], v132, s84, v[240:241]
	global_store_dwordx2 v[42:43], v[44:45], off
.LBB0_1443:
	s_or_b64 exec, exec, s[16:17]
	v_add_u32_e32 v42, 0x83, v212
	v_cmp_lt_i32_e64 s[16:17], s89, v212
	v_add_u32_e32 v133, s47, v42
	s_and_saveexec_b64 s[54:55], s[16:17]
	s_cbranch_execz .LBB0_1445
	v_pk_fma_f32 v[42:43], v[126:127], v[96:97], v[130:131]
	v_pk_fma_f32 v[44:45], v[124:125], v[94:95], v[128:129]
	v_pk_fma_f32 v[42:43], v[122:123], v[88:89], v[42:43]
	v_pk_fma_f32 v[44:45], v[120:121], v[86:87], v[44:45]
	v_pk_fma_f32 v[40:41], v[108:109], v[40:41], v[42:43]
	v_pk_fma_f32 v[38:39], v[106:107], v[38:39], v[44:45]
	v_pk_fma_f32 v[44:45], v[110:111], v[90:91], v[116:117]
	v_pk_mul_f32 v[46:47], v[40:41], v[40:41]
	v_pk_fma_f32 v[44:45], v[102:103], v[82:83], v[44:45]
	v_pk_mul_f32 v[48:49], v[38:39], v[38:39]
	v_mov_b64_e32 v[82:83], s[44:45]
	v_pk_fma_f32 v[46:47], v[46:47], s[42:43], v[82:83] op_sel_hi:[1,0,0] neg_lo:[1,0,0] neg_hi:[1,0,0]
	v_pk_fma_f32 v[48:49], v[48:49], s[42:43], v[82:83] op_sel_hi:[1,0,0] neg_lo:[1,0,0] neg_hi:[1,0,0]
	v_pk_mul_f32 v[46:47], v[40:41], v[46:47]
	v_pk_mul_f32 v[48:49], v[38:39], v[48:49]
	v_exp_f32_e32 v46, v46
	v_exp_f32_e32 v47, v47
	v_exp_f32_e32 v48, v48
	v_exp_f32_e32 v49, v49
	v_pk_fma_f32 v[42:43], v[112:113], v[92:93], v[118:119]
	v_pk_add_f32 v[46:47], v[46:47], 1.0 op_sel_hi:[1,0]
	v_pk_fma_f32 v[42:43], v[104:105], v[84:85], v[42:43]
	v_pk_add_f32 v[48:49], v[48:49], 1.0 op_sel_hi:[1,0]
	v_rcp_f32_e32 v46, v46
	v_rcp_f32_e32 v47, v47
	v_rcp_f32_e32 v48, v48
	v_rcp_f32_e32 v49, v49
	v_pk_fma_f32 v[36:37], v[100:101], v[36:37], v[42:43]
	v_pk_fma_f32 v[34:35], v[98:99], v[34:35], v[44:45]
	v_pk_mul_f32 v[40:41], v[40:41], v[46:47]
	v_pk_mul_f32 v[38:39], v[38:39], v[48:49]
	v_pk_mul_f32 v[36:37], v[36:37], v[40:41]
	v_pk_mul_f32 v[34:35], v[34:35], v[38:39]
	s_nop 0
	v_cvt_pk_f16_f32 v34, v34, v35
	v_cvt_pk_f16_f32 v35, v36, v37
	v_mad_i64_i32 v[36:37], s[94:95], v133, s84, v[240:241]
	global_store_dwordx2 v[36:37], v[34:35], off

; #define LAS __attribute__((address_space(3)))
; __device__ __forceinline__ unsigned pkh(float lo, float hi) { f32x2 v = {lo, hi}; h16x2 h = __builtin_convertvector(v, h16x2); return __builtin_bit_cast(unsigned, h); }
; __device__ __forceinline__ float dpp_shr1_keep(float keep, float v) { return __builtin_bit_cast(float, __builtin_amdgcn_update_dpp(__builtin_bit_cast(int, keep), __builtin_bit_cast(int, v), 0x111, 0xf, 0xf, false)); }
;     __device__ __forceinline__ void operator()(f32x4 (&acc)[2][2][4][2], const Unit& u, const Order& S, int wr, int wc, int fr_, int fq_, LAS unsigned char* xl, int ui) const {
;     ...
;                     if (g > 0) { r62 = *(const LAS f32x4*)(bnd + ((g - 1) * 2 + 0) * 256 + bj * HALF + tcol + 16 * n); r63 = *(const LAS f32x4*)(bnd + ((g - 1) * 2 + 1) * 256 + bj * HALF + tcol + 16 * n); }
;                     const f32x4 x0 = acc[ai][bj][0][n], x1 = acc[ai][bj][1][n], x2 = acc[ai][bj][2][n], x3 = acc[ai][bj][3][n];
;                     f32x4 pm1, pm2;
; #pragma unroll
;                     for (int e = 0; e < 4; ++e) { pm1[e] = dpp_shr1_keep(r63[e], x3[e]); pm2[e] = dpp_shr1_keep(r62[e], x2[e]); }
;                     h[0][bj] = __builtin_elementwise_fma(w0[bj], pm2, __builtin_elementwise_fma(w1[bj], pm1, __builtin_elementwise_fma(w2[bj], x0, bb[bj])));
;                     h[1][bj] = __builtin_elementwise_fma(w0[bj], pm1, __builtin_elementwise_fma(w1[bj], x0, __builtin_elementwise_fma(w2[bj], x1, bb[bj])));
;                     h[2][bj] = __builtin_elementwise_fma(w0[bj], x0, __builtin_elementwise_fma(w1[bj], x1, __builtin_elementwise_fma(w2[bj], x2, bb[bj])));
;                     h[3][bj] = __builtin_elementwise_fma(w0[bj], x1, __builtin_elementwise_fma(w1[bj], x2, __builtin_elementwise_fma(w2[bj], x3, bb[bj])));
;                 }
; #pragma unroll
;                 for (int m = 0; m < 4; ++m) {
;                     f32x4 o; { const f32x2 g0 = gelu_tanh2((f32x2){h[m][0][0], h[m][0][1]}) * (f32x2){h[m][1][0], h[m][1][1]}, g1 = gelu_tanh2((f32x2){h[m][0][2], h[m][0][3]}) * (f32x2){h[m][1][2], h[m][1][3]}; o = (f32x4){g0.x, g0.y, g1.x, g1.y}; }
;                     const int trow = trow0 + ai * HALF + m;
;                     if (trow >= lo) { u32x2 pk; pk.x = pkh(o[0], o[1]); pk.y = pkh(o[2], o[3]); *(u32x2*)(U + (size_t)(rs + trow) * FF + u.pn * HALF + tcol + 16 * n) = pk; }
.LBB0_1453:
	s_or_b64 exec, exec, s[2:3]
	v_mov_b32_e32 v115, v114
	v_mov_b32_e32 v50, v114
	v_mov_b32_e32 v51, v114
	v_pk_mul_f32 v[62:63], v[16:17], v[50:51]
	v_pk_mul_f32 v[64:65], v[14:15], v[114:115]
	ds_read_b128 v[14:17], v188 offset:3136
	v_pk_mul_f32 v[58:59], v[12:13], v[50:51]
	ds_read_b128 v[54:57], v188 offset:2112
	ds_read_b128 v[50:53], v188 offset:2624
	v_pk_mul_f32 v[60:61], v[10:11], v[114:115]
	ds_read_b128 v[10:13], v188 offset:3648
	s_waitcnt lgkmcnt(0)
	v_mov_b32_dpp v14, v30 row_shr:1 row_mask:0xf bank_mask:0xf
	v_mov_b32_dpp v54, v18 row_shr:1 row_mask:0xf bank_mask:0xf
	v_mov_b32_dpp v15, v31 row_shr:1 row_mask:0xf bank_mask:0xf
	v_mov_b32_dpp v55, v19 row_shr:1 row_mask:0xf bank_mask:0xf
	v_mov_b32_dpp v16, v32 row_shr:1 row_mask:0xf bank_mask:0xf
	v_mov_b32_dpp v56, v20 row_shr:1 row_mask:0xf bank_mask:0xf
	v_mov_b32_dpp v17, v33 row_shr:1 row_mask:0xf bank_mask:0xf
	v_mov_b32_dpp v57, v21 row_shr:1 row_mask:0xf bank_mask:0xf
	v_mov_b32_dpp v10, v26 row_shr:1 row_mask:0xf bank_mask:0xf
	v_mov_b32_dpp v50, v22 row_shr:1 row_mask:0xf bank_mask:0xf
	v_mov_b32_dpp v11, v27 row_shr:1 row_mask:0xf bank_mask:0xf
	v_mov_b32_dpp v51, v23 row_shr:1 row_mask:0xf bank_mask:0xf
	v_mov_b32_dpp v12, v28 row_shr:1 row_mask:0xf bank_mask:0xf
	v_mov_b32_dpp v52, v24 row_shr:1 row_mask:0xf bank_mask:0xf
	v_mov_b32_dpp v13, v29 row_shr:1 row_mask:0xf bank_mask:0xf
	v_mov_b32_dpp v53, v25 row_shr:1 row_mask:0xf bank_mask:0xf
	s_and_saveexec_b64 s[2:3], s[10:11]
	s_cbranch_execz .LBB0_1455
	v_pk_fma_f32 v[66:67], v[92:93], v[62:63], v[96:97]
	v_pk_fma_f32 v[68:69], v[90:91], v[64:65], v[94:95]
	v_pk_fma_f32 v[66:67], v[88:89], v[16:17], v[66:67]
	v_pk_fma_f32 v[68:69], v[86:87], v[14:15], v[68:69]
	v_pk_fma_f32 v[56:57], v[44:45], v[56:57], v[66:67]
	v_pk_fma_f32 v[54:55], v[42:43], v[54:55], v[68:69]
	v_pk_mul_f32 v[70:71], v[56:57], v[56:57]
	v_pk_mul_f32 v[72:73], v[54:55], v[54:55]
	v_mov_b64_e32 v[74:75], s[44:45]
	v_pk_fma_f32 v[70:71], v[70:71], s[42:43], v[74:75] op_sel_hi:[1,0,0] neg_lo:[1,0,0] neg_hi:[1,0,0]
	v_pk_fma_f32 v[72:73], v[72:73], s[42:43], v[74:75] op_sel_hi:[1,0,0] neg_lo:[1,0,0] neg_hi:[1,0,0]
	v_pk_mul_f32 v[70:71], v[56:57], v[70:71]
	v_pk_mul_f32 v[72:73], v[54:55], v[72:73]
	v_exp_f32_e32 v70, v70
	v_exp_f32_e32 v71, v71
	v_exp_f32_e32 v72, v72
	v_exp_f32_e32 v73, v73
	v_pk_fma_f32 v[66:67], v[48:49], v[58:59], v[84:85]
	v_pk_add_f32 v[70:71], v[70:71], 1.0 op_sel_hi:[1,0]
	v_pk_fma_f32 v[68:69], v[46:47], v[60:61], v[82:83]
	v_pk_add_f32 v[72:73], v[72:73], 1.0 op_sel_hi:[1,0]
	v_rcp_f32_e32 v70, v70
	v_rcp_f32_e32 v71, v71
	v_rcp_f32_e32 v72, v72
	v_rcp_f32_e32 v73, v73
	v_pk_fma_f32 v[66:67], v[40:41], v[12:13], v[66:67]
	v_pk_fma_f32 v[68:69], v[38:39], v[10:11], v[68:69]
	v_pk_fma_f32 v[52:53], v[36:37], v[52:53], v[66:67]
	v_pk_fma_f32 v[50:51], v[34:35], v[50:51], v[68:69]
	v_pk_mul_f32 v[56:57], v[56:57], v[70:71]
	v_pk_mul_f32 v[54:55], v[54:55], v[72:73]
	v_pk_mul_f32 v[52:53], v[52:53], v[56:57]
	v_pk_mul_f32 v[50:51], v[50:51], v[54:55]
	s_nop 0
	v_cvt_pk_f16_f32 v50, v50, v51
	v_cvt_pk_f16_f32 v51, v52, v53
	v_mad_i64_i32 v[52:53], s[4:5], v148, s84, v[240:241]
	global_store_dwordx2 v[52:53], v[50:51], off offset:32

; __device__ __forceinline__ unsigned pkh(float lo, float hi) { f32x2 v = {lo, hi}; h16x2 h = __builtin_convertvector(v, h16x2); return __builtin_bit_cast(unsigned, h); }
;     __device__ __forceinline__ void operator()(f32x4 (&acc)[2][2][4][2], const Unit& u, const Order& S, int wr, int wc, int fr_, int fq_, LAS unsigned char* xl, int ui) const {
;     ...
;                     h[0][bj] = __builtin_elementwise_fma(w0[bj], pm2, __builtin_elementwise_fma(w1[bj], pm1, __builtin_elementwise_fma(w2[bj], x0, bb[bj])));
;                     h[1][bj] = __builtin_elementwise_fma(w0[bj], pm1, __builtin_elementwise_fma(w1[bj], x0, __builtin_elementwise_fma(w2[bj], x1, bb[bj])));
;                     h[2][bj] = __builtin_elementwise_fma(w0[bj], x0, __builtin_elementwise_fma(w1[bj], x1, __builtin_elementwise_fma(w2[bj], x2, bb[bj])));
;                     h[3][bj] = __builtin_elementwise_fma(w0[bj], x1, __builtin_elementwise_fma(w1[bj], x2, __builtin_elementwise_fma(w2[bj], x3, bb[bj])));
;                 }
; #pragma unroll
;                 for (int m = 0; m < 4; ++m) {
;                     f32x4 o; { const f32x2 g0 = gelu_tanh2((f32x2){h[m][0][0], h[m][0][1]}) * (f32x2){h[m][1][0], h[m][1][1]}, g1 = gelu_tanh2((f32x2){h[m][0][2], h[m][0][3]}) * (f32x2){h[m][1][2], h[m][1][3]}; o = (f32x4){g0.x, g0.y, g1.x, g1.y}; }
;                     const int trow = trow0 + ai * HALF + m;
;                     if (trow >= lo) { u32x2 pk; pk.x = pkh(o[0], o[1]); pk.y = pkh(o[2], o[3]); *(u32x2*)(U + (size_t)(rs + trow) * FF + u.pn * HALF + tcol + 16 * n) = pk; }
.LBB0_1459:
	v_pk_fma_f32 v[116:117], v[92:93], v[72:73], v[96:97]
	v_pk_fma_f32 v[118:119], v[90:91], v[70:71], v[94:95]
	v_pk_fma_f32 v[116:117], v[88:89], v[104:105], v[116:117]
	v_pk_fma_f32 v[118:119], v[86:87], v[102:103], v[118:119]
	v_pk_fma_f32 v[108:109], v[44:45], v[108:109], v[116:117]
	v_pk_fma_f32 v[106:107], v[42:43], v[106:107], v[118:119]
	v_pk_mul_f32 v[120:121], v[108:109], v[108:109]
	v_pk_mul_f32 v[122:123], v[106:107], v[106:107]
	v_mov_b64_e32 v[124:125], s[44:45]
	v_pk_fma_f32 v[120:121], v[120:121], s[42:43], v[124:125] op_sel_hi:[1,0,0] neg_lo:[1,0,0] neg_hi:[1,0,0]
	v_pk_fma_f32 v[122:123], v[122:123], s[42:43], v[124:125] op_sel_hi:[1,0,0] neg_lo:[1,0,0] neg_hi:[1,0,0]
	v_pk_mul_f32 v[120:121], v[108:109], v[120:121]
	v_pk_mul_f32 v[122:123], v[106:107], v[122:123]
	v_exp_f32_e32 v120, v120
	v_exp_f32_e32 v121, v121
	v_exp_f32_e32 v122, v122
	v_exp_f32_e32 v123, v123
	v_pk_fma_f32 v[116:117], v[48:49], v[76:77], v[84:85]
	v_pk_add_f32 v[120:121], v[120:121], 1.0 op_sel_hi:[1,0]
	v_pk_fma_f32 v[118:119], v[46:47], v[74:75], v[82:83]
	v_pk_add_f32 v[122:123], v[122:123], 1.0 op_sel_hi:[1,0]
	v_rcp_f32_e32 v120, v120
	v_rcp_f32_e32 v121, v121
	v_rcp_f32_e32 v122, v122
	v_rcp_f32_e32 v123, v123
	v_pk_fma_f32 v[116:117], v[40:41], v[100:101], v[116:117]
	v_pk_fma_f32 v[118:119], v[38:39], v[98:99], v[118:119]
	v_pk_fma_f32 v[112:113], v[36:37], v[112:113], v[116:117]
	v_pk_fma_f32 v[110:111], v[34:35], v[110:111], v[118:119]
	v_pk_mul_f32 v[108:109], v[108:109], v[120:121]
	v_pk_mul_f32 v[106:107], v[106:107], v[122:123]
	v_pk_mul_f32 v[108:109], v[108:109], v[112:113]
	v_pk_mul_f32 v[106:107], v[106:107], v[110:111]
	s_nop 0
	v_cvt_pk_f16_f32 v106, v106, v107
	v_cvt_pk_f16_f32 v107, v108, v109
	v_mad_i64_i32 v[108:109], s[4:5], v213, s84, v[240:241]
	global_store_dwordx2 v[108:109], v[106:107], off offset:32
	s_or_b64 exec, exec, s[2:3]
	s_and_saveexec_b64 s[2:3], s[6:7]
	s_cbranch_execz .LBB0_1451
.LBB0_1460:
	v_pk_fma_f32 v[110:111], v[92:93], v[68:69], v[96:97]
	v_pk_fma_f32 v[112:113], v[90:91], v[66:67], v[94:95]
	v_pk_fma_f32 v[110:111], v[88:89], v[72:73], v[110:111]
	v_pk_fma_f32 v[112:113], v[86:87], v[70:71], v[112:113]
	v_pk_fma_f32 v[104:105], v[44:45], v[104:105], v[110:111]
	v_pk_fma_f32 v[102:103], v[42:43], v[102:103], v[112:113]
	v_pk_mul_f32 v[110:111], v[104:105], v[104:105]
	v_pk_mul_f32 v[112:113], v[102:103], v[102:103]
	v_mov_b64_e32 v[116:117], s[44:45]
	v_pk_fma_f32 v[110:111], v[110:111], s[42:43], v[116:117] op_sel_hi:[1,0,0] neg_lo:[1,0,0] neg_hi:[1,0,0]
	v_pk_fma_f32 v[112:113], v[112:113], s[42:43], v[116:117] op_sel_hi:[1,0,0] neg_lo:[1,0,0] neg_hi:[1,0,0]
	v_pk_mul_f32 v[110:111], v[104:105], v[110:111]
	v_pk_mul_f32 v[112:113], v[102:103], v[112:113]
	v_exp_f32_e32 v110, v110
	v_exp_f32_e32 v111, v111
	v_exp_f32_e32 v112, v112
	v_exp_f32_e32 v113, v113
	v_pk_fma_f32 v[106:107], v[48:49], v[80:81], v[84:85]
	v_pk_add_f32 v[110:111], v[110:111], 1.0 op_sel_hi:[1,0]
	v_pk_fma_f32 v[108:109], v[46:47], v[78:79], v[82:83]
	v_pk_add_f32 v[112:113], v[112:113], 1.0 op_sel_hi:[1,0]
	v_rcp_f32_e32 v110, v110
	v_rcp_f32_e32 v111, v111
	v_rcp_f32_e32 v112, v112
	v_rcp_f32_e32 v113, v113
	v_pk_fma_f32 v[106:107], v[40:41], v[76:77], v[106:107]
	v_pk_fma_f32 v[108:109], v[38:39], v[74:75], v[108:109]
	v_pk_fma_f32 v[100:101], v[36:37], v[100:101], v[106:107]
	v_pk_fma_f32 v[98:99], v[34:35], v[98:99], v[108:109]
	v_pk_mul_f32 v[104:105], v[104:105], v[110:111]
	v_pk_mul_f32 v[102:103], v[102:103], v[112:113]
	v_pk_mul_f32 v[100:101], v[104:105], v[100:101]
	v_pk_mul_f32 v[98:99], v[102:103], v[98:99]
	s_nop 0
	v_cvt_pk_f16_f32 v98, v98, v99
	v_cvt_pk_f16_f32 v99, v100, v101
	v_mad_i64_i32 v[100:101], s[4:5], v172, s84, v[240:241]
	global_store_dwordx2 v[100:101], v[98:99], off offset:32
	s_or_b64 exec, exec, s[2:3]
	s_and_saveexec_b64 s[2:3], s[8:9]
	s_cbranch_execnz .LBB0_1452
	s_branch .LBB0_1453
; __device__ __forceinline__ unsigned pkh(float lo, float hi) { f32x2 v = {lo, hi}; h16x2 h = __builtin_convertvector(v, h16x2); return __builtin_bit_cast(unsigned, h); }
;     __device__ __forceinline__ void operator()(f32x4 (&acc)[2][2][4][2], const Unit& u, const Order& S, int wr, int wc, int fr_, int fq_, LAS unsigned char* xl, int ui) const {
;     ...
;                     h[0][bj] = __builtin_elementwise_fma(w0[bj], pm2, __builtin_elementwise_fma(w1[bj], pm1, __builtin_elementwise_fma(w2[bj], x0, bb[bj])));
;                     h[1][bj] = __builtin_elementwise_fma(w0[bj], pm1, __builtin_elementwise_fma(w1[bj], x0, __builtin_elementwise_fma(w2[bj], x1, bb[bj])));
;                     h[2][bj] = __builtin_elementwise_fma(w0[bj], x0, __builtin_elementwise_fma(w1[bj], x1, __builtin_elementwise_fma(w2[bj], x2, bb[bj])));
;                     h[3][bj] = __builtin_elementwise_fma(w0[bj], x1, __builtin_elementwise_fma(w1[bj], x2, __builtin_elementwise_fma(w2[bj], x3, bb[bj])));
;                 }
; #pragma unroll
;                 for (int m = 0; m < 4; ++m) {
;                     f32x4 o; { const f32x2 g0 = gelu_tanh2((f32x2){h[m][0][0], h[m][0][1]}) * (f32x2){h[m][1][0], h[m][1][1]}, g1 = gelu_tanh2((f32x2){h[m][0][2], h[m][0][3]}) * (f32x2){h[m][1][2], h[m][1][3]}; o = (f32x4){g0.x, g0.y, g1.x, g1.y}; }
;                     const int trow = trow0 + ai * HALF + m;
;                     if (trow >= lo) { u32x2 pk; pk.x = pkh(o[0], o[1]); pk.y = pkh(o[2], o[3]); *(u32x2*)(U + (size_t)(rs + trow) * FF + u.pn * HALF + tcol + 16 * n) = pk; }
.LBB0_1461:
	v_pk_fma_f32 v[50:51], v[92:93], v[8:9], v[96:97]
	v_pk_fma_f32 v[52:53], v[90:91], v[6:7], v[94:95]
	v_pk_fma_f32 v[50:51], v[88:89], v[62:63], v[50:51]
	v_pk_fma_f32 v[52:53], v[86:87], v[64:65], v[52:53]
	v_pk_fma_f32 v[16:17], v[44:45], v[16:17], v[50:51]
	v_pk_fma_f32 v[14:15], v[42:43], v[14:15], v[52:53]
	v_pk_mul_f32 v[54:55], v[16:17], v[16:17]
	v_pk_mul_f32 v[56:57], v[14:15], v[14:15]
	v_mov_b64_e32 v[66:67], s[44:45]
	v_pk_fma_f32 v[54:55], v[54:55], s[42:43], v[66:67] op_sel_hi:[1,0,0] neg_lo:[1,0,0] neg_hi:[1,0,0]
	v_pk_fma_f32 v[56:57], v[56:57], s[42:43], v[66:67] op_sel_hi:[1,0,0] neg_lo:[1,0,0] neg_hi:[1,0,0]
	v_pk_mul_f32 v[54:55], v[16:17], v[54:55]
	v_pk_mul_f32 v[56:57], v[14:15], v[56:57]
	v_exp_f32_e32 v54, v54
	v_exp_f32_e32 v55, v55
	v_exp_f32_e32 v56, v56
	v_exp_f32_e32 v57, v57
	v_pk_fma_f32 v[50:51], v[48:49], v[4:5], v[84:85]
	v_pk_add_f32 v[54:55], v[54:55], 1.0 op_sel_hi:[1,0]
	v_pk_fma_f32 v[52:53], v[46:47], v[2:3], v[82:83]
	v_pk_add_f32 v[56:57], v[56:57], 1.0 op_sel_hi:[1,0]
	v_rcp_f32_e32 v54, v54
	v_rcp_f32_e32 v55, v55
	v_rcp_f32_e32 v56, v56
	v_rcp_f32_e32 v57, v57
	v_pk_fma_f32 v[50:51], v[40:41], v[58:59], v[50:51]
	v_pk_fma_f32 v[52:53], v[38:39], v[60:61], v[52:53]
	v_pk_fma_f32 v[12:13], v[36:37], v[12:13], v[50:51]
	v_pk_fma_f32 v[10:11], v[34:35], v[10:11], v[52:53]
	v_pk_mul_f32 v[16:17], v[16:17], v[54:55]
	v_pk_mul_f32 v[14:15], v[14:15], v[56:57]
	v_pk_mul_f32 v[12:13], v[12:13], v[16:17]
	v_pk_mul_f32 v[10:11], v[10:11], v[14:15]
	s_nop 0
	v_cvt_pk_f16_f32 v10, v10, v11
	v_cvt_pk_f16_f32 v11, v12, v13
	v_mad_i64_i32 v[12:13], s[4:5], v138, s84, v[240:241]
	global_store_dwordx2 v[12:13], v[10:11], off offset:32
	s_or_b64 exec, exec, s[2:3]
	s_and_saveexec_b64 s[2:3], s[14:15]
	s_cbranch_execz .LBB0_1457
.LBB0_1462:
	v_pk_fma_f32 v[10:11], v[92:93], v[20:21], v[96:97]
	v_pk_fma_f32 v[12:13], v[90:91], v[18:19], v[94:95]
	v_pk_fma_f32 v[10:11], v[88:89], v[8:9], v[10:11]
	v_pk_fma_f32 v[12:13], v[86:87], v[6:7], v[12:13]
	v_pk_fma_f32 v[10:11], v[44:45], v[62:63], v[10:11]
	v_pk_fma_f32 v[12:13], v[42:43], v[64:65], v[12:13]
	v_pk_mul_f32 v[50:51], v[10:11], v[10:11]
	v_pk_mul_f32 v[52:53], v[12:13], v[12:13]
	v_mov_b64_e32 v[54:55], s[44:45]
	v_pk_fma_f32 v[50:51], v[50:51], s[42:43], v[54:55] op_sel_hi:[1,0,0] neg_lo:[1,0,0] neg_hi:[1,0,0]
	v_pk_fma_f32 v[52:53], v[52:53], s[42:43], v[54:55] op_sel_hi:[1,0,0] neg_lo:[1,0,0] neg_hi:[1,0,0]
	v_pk_mul_f32 v[50:51], v[10:11], v[50:51]
	v_pk_mul_f32 v[52:53], v[12:13], v[52:53]
	v_exp_f32_e32 v50, v50
	v_exp_f32_e32 v51, v51
	v_exp_f32_e32 v52, v52
	v_exp_f32_e32 v53, v53
	v_pk_fma_f32 v[14:15], v[48:49], v[24:25], v[84:85]
	v_pk_add_f32 v[50:51], v[50:51], 1.0 op_sel_hi:[1,0]
	v_pk_fma_f32 v[16:17], v[46:47], v[22:23], v[82:83]
	v_pk_add_f32 v[52:53], v[52:53], 1.0 op_sel_hi:[1,0]
	v_rcp_f32_e32 v50, v50
	v_rcp_f32_e32 v51, v51
	v_rcp_f32_e32 v52, v52
	v_rcp_f32_e32 v53, v53
	v_pk_fma_f32 v[14:15], v[40:41], v[4:5], v[14:15]
	v_pk_fma_f32 v[16:17], v[38:39], v[2:3], v[16:17]
	v_pk_fma_f32 v[14:15], v[36:37], v[58:59], v[14:15]
	v_pk_fma_f32 v[16:17], v[34:35], v[60:61], v[16:17]
	v_pk_mul_f32 v[10:11], v[10:11], v[50:51]
	v_pk_mul_f32 v[12:13], v[12:13], v[52:53]
	v_pk_mul_f32 v[10:11], v[14:15], v[10:11]
	v_pk_mul_f32 v[12:13], v[16:17], v[12:13]
	s_nop 0
	v_cvt_pk_f16_f32 v12, v12, v13
	v_cvt_pk_f16_f32 v13, v10, v11
	v_mad_i64_i32 v[10:11], s[4:5], v132, s84, v[240:241]
	global_store_dwordx2 v[10:11], v[12:13], off offset:32
	s_or_b64 exec, exec, s[2:3]
	s_and_saveexec_b64 s[2:3], s[16:17]
	s_cbranch_execz .LBB0_1458
.LBB0_1463:
	v_pk_fma_f32 v[10:11], v[92:93], v[32:33], v[96:97]
	v_pk_fma_f32 v[12:13], v[90:91], v[30:31], v[94:95]
	v_pk_fma_f32 v[10:11], v[88:89], v[20:21], v[10:11]
	v_pk_fma_f32 v[12:13], v[86:87], v[18:19], v[12:13]
	v_pk_fma_f32 v[8:9], v[44:45], v[8:9], v[10:11]
	v_pk_fma_f32 v[6:7], v[42:43], v[6:7], v[12:13]
	v_pk_mul_f32 v[14:15], v[8:9], v[8:9]
	v_pk_mul_f32 v[16:17], v[6:7], v[6:7]
	v_mov_b64_e32 v[18:19], s[44:45]
	v_pk_fma_f32 v[14:15], v[14:15], s[42:43], v[18:19] op_sel_hi:[1,0,0] neg_lo:[1,0,0] neg_hi:[1,0,0]
	v_pk_fma_f32 v[16:17], v[16:17], s[42:43], v[18:19] op_sel_hi:[1,0,0] neg_lo:[1,0,0] neg_hi:[1,0,0]
	v_pk_mul_f32 v[14:15], v[8:9], v[14:15]
	v_pk_mul_f32 v[16:17], v[6:7], v[16:17]
	v_exp_f32_e32 v14, v14
	v_exp_f32_e32 v15, v15
	v_exp_f32_e32 v16, v16
	v_exp_f32_e32 v17, v17
	v_pk_fma_f32 v[10:11], v[48:49], v[28:29], v[84:85]
	v_pk_add_f32 v[14:15], v[14:15], 1.0 op_sel_hi:[1,0]
	v_pk_fma_f32 v[12:13], v[46:47], v[26:27], v[82:83]
	v_pk_add_f32 v[16:17], v[16:17], 1.0 op_sel_hi:[1,0]
	v_rcp_f32_e32 v14, v14
	v_rcp_f32_e32 v15, v15
	v_rcp_f32_e32 v16, v16
	v_rcp_f32_e32 v17, v17
	v_pk_fma_f32 v[10:11], v[40:41], v[24:25], v[10:11]
	v_pk_fma_f32 v[12:13], v[38:39], v[22:23], v[12:13]
	v_pk_fma_f32 v[4:5], v[36:37], v[4:5], v[10:11]
	v_pk_fma_f32 v[2:3], v[34:35], v[2:3], v[12:13]
	v_pk_mul_f32 v[8:9], v[8:9], v[14:15]
	v_pk_mul_f32 v[6:7], v[6:7], v[16:17]
	v_pk_mul_f32 v[4:5], v[4:5], v[8:9]
	v_pk_mul_f32 v[2:3], v[2:3], v[6:7]
	s_nop 0
	v_cvt_pk_f16_f32 v2, v2, v3
	v_cvt_pk_f16_f32 v3, v4, v5
	v_mad_i64_i32 v[4:5], s[4:5], v133, s84, v[240:241]
	global_store_dwordx2 v[4:5], v[2:3], off offset:32
	s_or_b64 exec, exec, s[2:3]
	s_andn2_b64 vcc, exec, s[0:1]
	s_mov_b64 s[0:1], -1
	s_cbranch_vccnz .LBB0_1402
